# lazy LayerNorm: LN of layers 0-2 writes XB + per-row (mean,rstd) instead of the f32 stream; out epilogue of layers 1-3 re-applies (x-mean)*rstd*gamma+beta in the same f32 op order before ALPHA*x+acc
# speedup vs baseline: 1.1035x; 1.0096x over previous
; #define PG8_STAGE(bufoff, gbase, voff) do { _Pragma("unroll") for (int _i = 0; _i < 2; ++_i) \
;         __builtin_amdgcn_global_load_lds((const unsigned*)((const char*)(gbase) + (voff)[_i]), (PG8_LAS unsigned*)(lds + (bufoff) + ldsw + _i * 8192), 16, 0, 0); } while (0)
; #define PG8_LDA(dst, b, h) do { _Pragma("unroll") for (int m = 0; m < 4; ++m) _Pragma("unroll") for (int k = 0; k < 2; ++k) dst[m][k] = *(const PG8_LAS bf16x8*)(lds + PG8_SA(b, h) + aoff + m * 2048 + k * 1024); } while (0)
; #define PG8_LDB(dst, b, h) do { _Pragma("unroll") for (int n = 0; n < 2; ++n) _Pragma("unroll") for (int k = 0; k < 2; ++k) dst[n][k] = *(const PG8_LAS bf16x8*)(lds + PG8_SB(b, h) + boff + n * 2048 + k * 1024); } while (0)
; #define PG8_MMA(ai, bj, At, Bt) do { __builtin_amdgcn_s_setprio(1); _Pragma("unroll") for (int m = 0; m < 4; ++m) _Pragma("unroll") for (int n = 0; n < 2; ++n) _Pragma("unroll") for (int k = 0; k < 2; ++k) \
;         acc[ai][bj][m][n] = __builtin_amdgcn_mfma_f32_16x16x32_bf16(Bt[n][k], At[m][k], acc[ai][bj][m][n], 0, 0, 0); __builtin_amdgcn_s_setprio(0); } while (0)
; #define PG8_WAIT_V(n) asm volatile("s_waitcnt vmcnt(" #n ")" ::: "memory")
; #define PG8_WAIT_L(n) asm volatile("s_waitcnt lgkmcnt(" #n ")" ::: "memory")
; #define PG8_BAR __builtin_amdgcn_s_barrier()
; #define PG8_SCHED __builtin_amdgcn_sched_barrier(0)
; template <class Epi, class Sched>
; __device__ __forceinline__ void gemm_phase(PG8_LAS unsigned char* lds, const Gemm g, const Sched& S, const Epi& E) {
;     ...
;             PG8_LDB(B0, 0, 0); PG8_SCHED; PG8_LDA(At, 0, 0); PG8_STAGE(PG8_SA(1, 1), a1 + hstep, voffA);
;             PG8_WAIT_L(8); PG8_BAR; PG8_WAIT_L(0); PG8_MMA(0, 0, At, B0); PG8_BAR; PG8_SCHED;
;             PG8_LDB(B1, 0, 1); PG8_STAGE(PG8_SB(0, 0), b2, voffB);
;             PG8_BAR; PG8_WAIT_L(0); PG8_MMA(0, 1, At, B1); PG8_BAR;
;             PG8_LDA(At, 0, 1); PG8_STAGE(PG8_SA(0, 0), a2, voffA);
;             PG8_BAR; PG8_WAIT_L(0); PG8_MMA(1, 0, At, B0); PG8_BAR; PG8_SCHED;
;             PG8_STAGE(PG8_SB(0, 1), b2 + hstep, voffB);
;             PG8_WAIT_V(6); PG8_BAR; PG8_MMA(1, 1, At, B1); PG8_BAR;
.LBB0_2754:
	s_add_u32 s14, s12, 0xfffc0080
	s_addc_u32 s15, s13, -1
	s_add_i32 s37, 0, 0x10000
	v_add_u32_e32 v140, s37, v142
	ds_read_b128 v[144:147], v140
	ds_read_b128 v[148:151], v140 offset:1024
	ds_read_b128 v[162:165], v140 offset:2048
	ds_read_b128 v[166:169], v140 offset:3072
	s_cmp_eq_u32 s36, 12
	s_cselect_b32 s17, s5, s15
	s_cselect_b32 s16, s31, s14
	s_cselect_b32 s15, s3, s35
	s_cselect_b32 s14, s33, s34
	v_lshl_add_u64 v[140:141], s[12:13], 0, v[136:137]
	s_add_i32 m0, s23, 0xc000
	ds_read_b128 v[170:173], v143
	ds_read_b128 v[174:177], v143 offset:1024
	ds_read_b128 v[178:181], v143 offset:2048
	ds_read_b128 v[188:191], v143 offset:3072
	ds_read_b128 v[192:195], v143 offset:4096
	ds_read_b128 v[196:199], v143 offset:5120
	ds_read_b128 v[200:203], v143 offset:6144
	ds_read_b128 v[204:207], v143 offset:7168
	global_load_lds_dwordx4 v[140:141], off
	v_lshl_add_u64 v[140:141], s[12:13], 0, v[138:139]
	s_add_i32 m0, s23, 0xe000
	s_nop 0
	global_load_lds_dwordx4 v[140:141], off
	s_waitcnt lgkmcnt(8)
	s_barrier
	s_waitcnt lgkmcnt(0)
	s_setprio 1
	s_waitcnt lgkmcnt(0)
	v_mfma_f32_16x16x32_bf16 v[130:133], v[144:147], v[170:173], v[130:133]
	v_mfma_f32_16x16x32_bf16 v[126:129], v[162:165], v[170:173], v[126:129]
	v_mfma_f32_16x16x32_bf16 v[114:117], v[144:147], v[178:181], v[114:117]
	v_mfma_f32_16x16x32_bf16 v[110:113], v[162:165], v[178:181], v[110:113]
	v_mfma_f32_16x16x32_bf16 v[98:101], v[144:147], v[192:195], v[98:101]
	v_mfma_f32_16x16x32_bf16 v[94:97], v[162:165], v[192:195], v[94:97]
	v_mfma_f32_16x16x32_bf16 v[82:85], v[144:147], v[200:203], v[82:85]
	v_mfma_f32_16x16x32_bf16 v[78:81], v[162:165], v[200:203], v[78:81]
	v_mfma_f32_16x16x32_bf16 v[130:133], v[148:151], v[174:177], v[130:133]
	v_mfma_f32_16x16x32_bf16 v[126:129], v[166:169], v[174:177], v[126:129]
	v_mfma_f32_16x16x32_bf16 v[114:117], v[148:151], v[188:191], v[114:117]
	v_mfma_f32_16x16x32_bf16 v[110:113], v[166:169], v[188:191], v[110:113]
	v_mfma_f32_16x16x32_bf16 v[98:101], v[148:151], v[196:199], v[98:101]
	v_mfma_f32_16x16x32_bf16 v[94:97], v[166:169], v[196:199], v[94:97]
	v_mfma_f32_16x16x32_bf16 v[82:85], v[148:151], v[204:207], v[82:85]
	v_mfma_f32_16x16x32_bf16 v[78:81], v[166:169], v[204:207], v[78:81]
	s_setprio 0
	s_barrier
	s_add_i32 s40, 0, 0x14000
	v_add_u32_e32 v140, s40, v142
	s_add_i32 s37, s37, s21
	ds_read_b128 v[208:211], v140
	ds_read_b128 v[212:215], v140 offset:1024
	ds_read_b128 v[216:219], v140 offset:2048
	ds_read_b128 v[220:223], v140 offset:3072
	v_lshl_add_u64 v[140:141], s[14:15], 0, v[134:135]
	s_mov_b32 m0, s37
	v_lshl_add_u64 v[154:155], s[14:15], 0, v[18:19]
	global_load_lds_dwordx4 v[140:141], off
	s_add_i32 m0, s37, 0x2000
	s_nop 0
	global_load_lds_dwordx4 v[154:155], off
	s_barrier
	s_waitcnt lgkmcnt(0)
	s_setprio 1
	s_waitcnt lgkmcnt(0)
	v_mfma_f32_16x16x32_bf16 v[122:125], v[208:211], v[170:173], v[122:125]
	v_mfma_f32_16x16x32_bf16 v[118:121], v[216:219], v[170:173], v[118:121]
	v_mfma_f32_16x16x32_bf16 v[106:109], v[208:211], v[178:181], v[106:109]
	v_mfma_f32_16x16x32_bf16 v[102:105], v[216:219], v[178:181], v[102:105]
	v_mfma_f32_16x16x32_bf16 v[90:93], v[208:211], v[192:195], v[90:93]
	v_mfma_f32_16x16x32_bf16 v[86:89], v[216:219], v[192:195], v[86:89]
	v_mfma_f32_16x16x32_bf16 v[74:77], v[208:211], v[200:203], v[74:77]
	v_mfma_f32_16x16x32_bf16 v[70:73], v[216:219], v[200:203], v[70:73]
	v_mfma_f32_16x16x32_bf16 v[122:125], v[212:215], v[174:177], v[122:125]
	v_mfma_f32_16x16x32_bf16 v[118:121], v[220:223], v[174:177], v[118:121]
	v_mfma_f32_16x16x32_bf16 v[106:109], v[212:215], v[188:191], v[106:109]
	v_mfma_f32_16x16x32_bf16 v[102:105], v[220:223], v[188:191], v[102:105]
	v_mfma_f32_16x16x32_bf16 v[90:93], v[212:215], v[196:199], v[90:93]
	v_mfma_f32_16x16x32_bf16 v[86:89], v[220:223], v[196:199], v[86:89]
	v_mfma_f32_16x16x32_bf16 v[74:77], v[212:215], v[204:207], v[74:77]
	v_mfma_f32_16x16x32_bf16 v[70:73], v[220:223], v[204:207], v[70:73]
	s_setprio 0
	s_mov_b32 m0, s23
	v_lshl_add_u64 v[156:157], s[16:17], 0, v[134:135]
	s_barrier
	ds_read_b128 v[170:173], v143 offset:16384
	ds_read_b128 v[174:177], v143 offset:17408
	ds_read_b128 v[178:181], v143 offset:18432
	ds_read_b128 v[188:191], v143 offset:19456
	ds_read_b128 v[192:195], v143 offset:20480
	ds_read_b128 v[196:199], v143 offset:21504
	ds_read_b128 v[200:203], v143 offset:22528
	ds_read_b128 v[204:207], v143 offset:23552
	global_load_lds_dwordx4 v[156:157], off
	v_lshl_add_u64 v[186:187], s[16:17], 0, v[18:19]
	s_mov_b32 m0, s24
	s_nop 0
	global_load_lds_dwordx4 v[186:187], off
	s_barrier
	s_waitcnt lgkmcnt(0)
	s_setprio 1
	s_waitcnt lgkmcnt(0)
	v_mfma_f32_16x16x32_bf16 v[66:69], v[144:147], v[170:173], v[66:69]
	v_mfma_f32_16x16x32_bf16 v[62:65], v[162:165], v[170:173], v[62:65]
	v_mfma_f32_16x16x32_bf16 v[50:53], v[144:147], v[178:181], v[50:53]
	v_mfma_f32_16x16x32_bf16 v[46:49], v[162:165], v[178:181], v[46:49]
	v_mfma_f32_16x16x32_bf16 v[34:37], v[144:147], v[192:195], v[34:37]
	v_mfma_f32_16x16x32_bf16 v[30:33], v[162:165], v[192:195], v[30:33]
	v_mfma_f32_16x16x32_bf16 v[12:15], v[144:147], v[200:203], v[12:15]
	v_mfma_f32_16x16x32_bf16 v[8:11], v[162:165], v[200:203], v[8:11]
	v_mfma_f32_16x16x32_bf16 v[66:69], v[148:151], v[174:177], v[66:69]
	v_mfma_f32_16x16x32_bf16 v[62:65], v[166:169], v[174:177], v[62:65]
	v_mfma_f32_16x16x32_bf16 v[50:53], v[148:151], v[188:191], v[50:53]
	v_mfma_f32_16x16x32_bf16 v[46:49], v[166:169], v[188:191], v[46:49]
	v_mfma_f32_16x16x32_bf16 v[34:37], v[148:151], v[196:199], v[34:37]
	v_mfma_f32_16x16x32_bf16 v[30:33], v[166:169], v[196:199], v[30:33]
	v_mfma_f32_16x16x32_bf16 v[12:15], v[148:151], v[204:207], v[12:15]
	v_mfma_f32_16x16x32_bf16 v[8:11], v[166:169], v[204:207], v[8:11]
	s_setprio 0
	s_barrier
; #define PG8_STAGE(bufoff, gbase, voff) do { _Pragma("unroll") for (int _i = 0; _i < 2; ++_i) \
;         __builtin_amdgcn_global_load_lds((const unsigned*)((const char*)(gbase) + (voff)[_i]), (PG8_LAS unsigned*)(lds + (bufoff) + ldsw + _i * 8192), 16, 0, 0); } while (0)
; #define PG8_LDA(dst, b, h) do { _Pragma("unroll") for (int m = 0; m < 4; ++m) _Pragma("unroll") for (int k = 0; k < 2; ++k) dst[m][k] = *(const PG8_LAS bf16x8*)(lds + PG8_SA(b, h) + aoff + m * 2048 + k * 1024); } while (0)
; #define PG8_LDB(dst, b, h) do { _Pragma("unroll") for (int n = 0; n < 2; ++n) _Pragma("unroll") for (int k = 0; k < 2; ++k) dst[n][k] = *(const PG8_LAS bf16x8*)(lds + PG8_SB(b, h) + boff + n * 2048 + k * 1024); } while (0)
; #define PG8_MMA(ai, bj, At, Bt) do { __builtin_amdgcn_s_setprio(1); _Pragma("unroll") for (int m = 0; m < 4; ++m) _Pragma("unroll") for (int n = 0; n < 2; ++n) _Pragma("unroll") for (int k = 0; k < 2; ++k) \
;         acc[ai][bj][m][n] = __builtin_amdgcn_mfma_f32_16x16x32_bf16(Bt[n][k], At[m][k], acc[ai][bj][m][n], 0, 0, 0); __builtin_amdgcn_s_setprio(0); } while (0)
; #define PG8_WAIT_V(n) asm volatile("s_waitcnt vmcnt(" #n ")" ::: "memory")
; #define PG8_WAIT_L(n) asm volatile("s_waitcnt lgkmcnt(" #n ")" ::: "memory")
; #define PG8_BAR __builtin_amdgcn_s_barrier()
; #define PG8_SCHED __builtin_amdgcn_sched_barrier(0)
; template <class Epi, class Sched>
; __device__ __forceinline__ void gemm_phase(PG8_LAS unsigned char* lds, const Gemm g, const Sched& S, const Epi& E) {
;     ...
;             PG8_WAIT_V(6); PG8_BAR; PG8_MMA(1, 1, At, B1); PG8_BAR;
;             PG8_LDB(B0, 1, 0); PG8_SCHED; PG8_LDA(At, 1, 0); PG8_STAGE(PG8_SA(0, 1), a2 + hstep, voffA);
;             PG8_WAIT_L(8); PG8_BAR; PG8_WAIT_L(0); PG8_MMA(0, 0, At, B0); PG8_BAR; PG8_SCHED;
;             PG8_LDB(B1, 1, 1); PG8_STAGE(PG8_SB(1, 0), b3, voffB);
;             PG8_BAR; PG8_WAIT_L(0); PG8_MMA(0, 1, At, B1); PG8_BAR;
;             PG8_LDA(At, 1, 1); PG8_STAGE(PG8_SA(1, 0), a3, voffA);
;             PG8_BAR; PG8_WAIT_L(0); PG8_MMA(1, 0, At, B0); PG8_BAR; PG8_SCHED;
	s_add_u32 s38, s14, 0x40000
	s_addc_u32 s39, s15, 0
	s_add_i32 s37, s40, s21
	v_lshl_add_u64 v[144:145], s[38:39], 0, v[134:135]
	s_mov_b32 m0, s37
	s_nop 0
	global_load_lds_dwordx4 v[144:145], off
	v_lshl_add_u64 v[144:145], s[38:39], 0, v[18:19]
	s_add_i32 m0, s37, 0x2000
	s_nop 0
	global_load_lds_dwordx4 v[144:145], off
	s_waitcnt vmcnt(6)
	s_barrier
	s_setprio 1
	v_mfma_f32_16x16x32_bf16 v[58:61], v[208:211], v[170:173], v[58:61]
	v_mfma_f32_16x16x32_bf16 v[54:57], v[216:219], v[170:173], v[54:57]
	v_mfma_f32_16x16x32_bf16 v[42:45], v[208:211], v[178:181], v[42:45]
	v_mfma_f32_16x16x32_bf16 v[38:41], v[216:219], v[178:181], v[38:41]
	v_mfma_f32_16x16x32_bf16 v[26:29], v[208:211], v[192:195], v[26:29]
	v_mfma_f32_16x16x32_bf16 v[22:25], v[216:219], v[192:195], v[22:25]
	v_mfma_f32_16x16x32_bf16 v[4:7], v[208:211], v[200:203], v[4:7]
	v_mfma_f32_16x16x32_bf16 v[0:3], v[216:219], v[200:203], v[0:3]
	v_mfma_f32_16x16x32_bf16 v[58:61], v[212:215], v[174:177], v[58:61]
	v_mfma_f32_16x16x32_bf16 v[54:57], v[220:223], v[174:177], v[54:57]
	v_mfma_f32_16x16x32_bf16 v[42:45], v[212:215], v[188:191], v[42:45]
	v_mfma_f32_16x16x32_bf16 v[38:41], v[220:223], v[188:191], v[38:41]
	v_mfma_f32_16x16x32_bf16 v[26:29], v[212:215], v[196:199], v[26:29]
	v_mfma_f32_16x16x32_bf16 v[22:25], v[220:223], v[196:199], v[22:25]
	v_mfma_f32_16x16x32_bf16 v[4:7], v[212:215], v[204:207], v[4:7]
	v_mfma_f32_16x16x32_bf16 v[0:3], v[220:223], v[204:207], v[0:3]
	s_setprio 0
	s_add_i32 s37, 0, 0x18000
	v_add_u32_e32 v166, s37, v142
	s_barrier
	ds_read_b128 v[144:147], v166
	ds_read_b128 v[148:151], v166 offset:1024
	ds_read_b128 v[162:165], v166 offset:2048
	ds_read_b128 v[166:169], v166 offset:3072
	s_add_u32 s16, s16, 0x40000
	s_addc_u32 s17, s17, 0
	s_mov_b32 m0, s25
	v_lshl_add_u64 v[208:209], s[16:17], 0, v[134:135]
	ds_read_b128 v[170:173], v143 offset:32768
	ds_read_b128 v[174:177], v143 offset:33792
	ds_read_b128 v[178:181], v143 offset:34816
	ds_read_b128 v[188:191], v143 offset:35840
	ds_read_b128 v[192:195], v143 offset:36864
	ds_read_b128 v[196:199], v143 offset:37888
	ds_read_b128 v[200:203], v143 offset:38912
	ds_read_b128 v[204:207], v143 offset:39936
	global_load_lds_dwordx4 v[208:209], off
	v_lshl_add_u64 v[208:209], s[16:17], 0, v[18:19]
	s_mov_b32 m0, s26
	s_nop 0
	global_load_lds_dwordx4 v[208:209], off
	s_waitcnt lgkmcnt(8)
	s_barrier
	s_waitcnt lgkmcnt(0)
	s_setprio 1
	s_waitcnt lgkmcnt(0)
	v_mfma_f32_16x16x32_bf16 v[130:133], v[144:147], v[170:173], v[130:133]
	v_mfma_f32_16x16x32_bf16 v[126:129], v[162:165], v[170:173], v[126:129]
	v_mfma_f32_16x16x32_bf16 v[114:117], v[144:147], v[178:181], v[114:117]
	v_mfma_f32_16x16x32_bf16 v[110:113], v[162:165], v[178:181], v[110:113]
	v_mfma_f32_16x16x32_bf16 v[98:101], v[144:147], v[192:195], v[98:101]
	v_mfma_f32_16x16x32_bf16 v[94:97], v[162:165], v[192:195], v[94:97]
	v_mfma_f32_16x16x32_bf16 v[82:85], v[144:147], v[200:203], v[82:85]
	v_mfma_f32_16x16x32_bf16 v[78:81], v[162:165], v[200:203], v[78:81]
	v_mfma_f32_16x16x32_bf16 v[130:133], v[148:151], v[174:177], v[130:133]
	v_mfma_f32_16x16x32_bf16 v[126:129], v[166:169], v[174:177], v[126:129]
	v_mfma_f32_16x16x32_bf16 v[114:117], v[148:151], v[188:191], v[114:117]
	v_mfma_f32_16x16x32_bf16 v[110:113], v[166:169], v[188:191], v[110:113]
	v_mfma_f32_16x16x32_bf16 v[98:101], v[148:151], v[196:199], v[98:101]
	v_mfma_f32_16x16x32_bf16 v[94:97], v[166:169], v[196:199], v[94:97]
	v_mfma_f32_16x16x32_bf16 v[82:85], v[148:151], v[204:207], v[82:85]
	v_mfma_f32_16x16x32_bf16 v[78:81], v[166:169], v[204:207], v[78:81]
	s_setprio 0
	s_barrier
	s_add_i32 s16, 0, 0x1c000
	s_add_i32 s17, s37, s21
	v_add_u32_e32 v220, s16, v142
	v_lshl_add_u64 v[140:141], v[140:141], 0, s[42:43]
	s_mov_b32 m0, s17
	ds_read_b128 v[208:211], v220
	ds_read_b128 v[212:215], v220 offset:1024
	ds_read_b128 v[216:219], v220 offset:2048
	ds_read_b128 v[220:223], v220 offset:3072
	global_load_lds_dwordx4 v[140:141], off
	v_lshl_add_u64 v[140:141], v[154:155], 0, s[42:43]
	s_add_i32 m0, s17, 0x2000
	s_nop 0
	global_load_lds_dwordx4 v[140:141], off
	s_barrier
	s_waitcnt lgkmcnt(0)
	s_setprio 1
	s_waitcnt lgkmcnt(0)
	v_mfma_f32_16x16x32_bf16 v[122:125], v[208:211], v[170:173], v[122:125]
	v_mfma_f32_16x16x32_bf16 v[118:121], v[216:219], v[170:173], v[118:121]
	v_mfma_f32_16x16x32_bf16 v[106:109], v[208:211], v[178:181], v[106:109]
	v_mfma_f32_16x16x32_bf16 v[102:105], v[216:219], v[178:181], v[102:105]
	v_mfma_f32_16x16x32_bf16 v[90:93], v[208:211], v[192:195], v[90:93]
	v_mfma_f32_16x16x32_bf16 v[86:89], v[216:219], v[192:195], v[86:89]
	v_mfma_f32_16x16x32_bf16 v[74:77], v[208:211], v[200:203], v[74:77]
	v_mfma_f32_16x16x32_bf16 v[70:73], v[216:219], v[200:203], v[70:73]
	v_mfma_f32_16x16x32_bf16 v[122:125], v[212:215], v[174:177], v[122:125]
	v_mfma_f32_16x16x32_bf16 v[118:121], v[220:223], v[174:177], v[118:121]
	v_mfma_f32_16x16x32_bf16 v[106:109], v[212:215], v[188:191], v[106:109]
	v_mfma_f32_16x16x32_bf16 v[102:105], v[220:223], v[188:191], v[102:105]
	v_mfma_f32_16x16x32_bf16 v[90:93], v[212:215], v[196:199], v[90:93]
	v_mfma_f32_16x16x32_bf16 v[86:89], v[220:223], v[196:199], v[86:89]
	v_mfma_f32_16x16x32_bf16 v[74:77], v[212:215], v[204:207], v[74:77]
	v_mfma_f32_16x16x32_bf16 v[70:73], v[220:223], v[204:207], v[70:73]
	s_setprio 0
	s_mov_b32 m0, s27
	v_lshl_add_u64 v[140:141], v[156:157], 0, s[42:43]
	s_barrier
	ds_read_b128 v[170:173], v143 offset:49152
	ds_read_b128 v[174:177], v143 offset:50176
	ds_read_b128 v[178:181], v143 offset:51200
	ds_read_b128 v[188:191], v143 offset:52224
	ds_read_b128 v[192:195], v143 offset:53248
	ds_read_b128 v[196:199], v143 offset:54272
	ds_read_b128 v[200:203], v143 offset:55296
	ds_read_b128 v[204:207], v143 offset:56320
	global_load_lds_dwordx4 v[140:141], off
	v_lshl_add_u64 v[140:141], v[186:187], 0, s[42:43]
	s_mov_b32 m0, s28
	s_nop 0
	global_load_lds_dwordx4 v[140:141], off
	s_barrier
; DI bf16x4 pack4(float a, float b, float c, float d) { u32x2v u; u.x = pk2(a, b); u.y = pk2(c, d); return __builtin_bit_cast(bf16x4, u); }
; #define PG8_STAGE(bufoff, gbase, voff) do { _Pragma("unroll") for (int _i = 0; _i < 2; ++_i) \
;         __builtin_amdgcn_global_load_lds((const unsigned*)((const char*)(gbase) + (voff)[_i]), (PG8_LAS unsigned*)(lds + (bufoff) + ldsw + _i * 8192), 16, 0, 0); } while (0)
; #define PG8_MMA(ai, bj, At, Bt) do { __builtin_amdgcn_s_setprio(1); _Pragma("unroll") for (int m = 0; m < 4; ++m) _Pragma("unroll") for (int n = 0; n < 2; ++n) _Pragma("unroll") for (int k = 0; k < 2; ++k) \
;         acc[ai][bj][m][n] = __builtin_amdgcn_mfma_f32_16x16x32_bf16(Bt[n][k], At[m][k], acc[ai][bj][m][n], 0, 0, 0); __builtin_amdgcn_s_setprio(0); } while (0)
; #define PG8_WAIT_V(n) asm volatile("s_waitcnt vmcnt(" #n ")" ::: "memory")
; #define PG8_WAIT_L(n) asm volatile("s_waitcnt lgkmcnt(" #n ")" ::: "memory")
; #define PG8_BAR __builtin_amdgcn_s_barrier()
; #define PG8_SCHED __builtin_amdgcn_sched_barrier(0)
; template <class Epi, class Sched>
; __device__ __forceinline__ void gemm_phase(PG8_LAS unsigned char* lds, const Gemm g, const Sched& S, const Epi& E) {
;     ...
;             PG8_BAR; PG8_WAIT_L(0); PG8_MMA(1, 0, At, B0); PG8_BAR; PG8_SCHED;
;             PG8_STAGE(PG8_SB(1, 1), b3 + hstep, voffB);
;             PG8_WAIT_V(6); PG8_BAR; PG8_MMA(1, 1, At, B1); PG8_BAR;
;         }
;         if constexpr (!Epi::AFTER_DRAIN) { E(acc, cur, wr, wc, fr, fq); S.done(cur); }
;   DI void operator()(const f32x4 (&acc)[2][2][4][2], const pg8::Unit& u, int wr, int wc, int fr, int fq) const {
;     ...
;             if (MODE == 0) {
;               const unsigned g = *reinterpret_cast<const unsigned*>(reinterpret_cast<const unsigned char*>(p.ws + OFF_RB) + idx);
;               const float k = 1.f / 255.f;
;               st4(MERGED + idx, pack4((float)(g & 255u) * k * a[0], (float)((g >> 8) & 255u) * k * a[1], (float)((g >> 16) & 255u) * k * a[2], (float)(g >> 24) * k * a[3]));
;             } else {
;               f32x4 x = *reinterpret_cast<const f32x4*>(p.out + idx);
;               x = x * ALPHA + a;
;               *reinterpret_cast<f32x4*>(p.out + idx) = x;
;             }
	s_waitcnt lgkmcnt(0)
	s_setprio 1
	s_waitcnt lgkmcnt(0)
	v_mfma_f32_16x16x32_bf16 v[66:69], v[144:147], v[170:173], v[66:69]
	v_mfma_f32_16x16x32_bf16 v[62:65], v[162:165], v[170:173], v[62:65]
	v_mfma_f32_16x16x32_bf16 v[50:53], v[144:147], v[178:181], v[50:53]
	v_mfma_f32_16x16x32_bf16 v[46:49], v[162:165], v[178:181], v[46:49]
	v_mfma_f32_16x16x32_bf16 v[34:37], v[144:147], v[192:195], v[34:37]
	v_mfma_f32_16x16x32_bf16 v[30:33], v[162:165], v[192:195], v[30:33]
	v_mfma_f32_16x16x32_bf16 v[12:15], v[144:147], v[200:203], v[12:15]
	v_mfma_f32_16x16x32_bf16 v[8:11], v[162:165], v[200:203], v[8:11]
	v_mfma_f32_16x16x32_bf16 v[66:69], v[148:151], v[174:177], v[66:69]
	v_mfma_f32_16x16x32_bf16 v[62:65], v[166:169], v[174:177], v[62:65]
	v_mfma_f32_16x16x32_bf16 v[50:53], v[148:151], v[188:191], v[50:53]
	v_mfma_f32_16x16x32_bf16 v[46:49], v[166:169], v[188:191], v[46:49]
	v_mfma_f32_16x16x32_bf16 v[34:37], v[148:151], v[196:199], v[34:37]
	v_mfma_f32_16x16x32_bf16 v[30:33], v[166:169], v[196:199], v[30:33]
	v_mfma_f32_16x16x32_bf16 v[12:15], v[148:151], v[204:207], v[12:15]
	v_mfma_f32_16x16x32_bf16 v[8:11], v[166:169], v[204:207], v[8:11]
	s_setprio 0
	s_barrier
	s_add_u32 s14, s14, 0x40080
	s_addc_u32 s15, s15, 0
	s_add_i32 s16, s16, s21
	v_lshl_add_u64 v[140:141], s[14:15], 0, v[134:135]
	s_mov_b32 m0, s16
	s_nop 0
	global_load_lds_dwordx4 v[140:141], off
	v_lshl_add_u64 v[140:141], s[14:15], 0, v[18:19]
	s_add_i32 m0, s16, 0x2000
	s_nop 0
	global_load_lds_dwordx4 v[140:141], off
	s_waitcnt vmcnt(6)
	s_barrier
	s_setprio 1
	v_mfma_f32_16x16x32_bf16 v[58:61], v[208:211], v[170:173], v[58:61]
	v_mfma_f32_16x16x32_bf16 v[54:57], v[216:219], v[170:173], v[54:57]
	v_mfma_f32_16x16x32_bf16 v[42:45], v[208:211], v[178:181], v[42:45]
	v_mfma_f32_16x16x32_bf16 v[38:41], v[216:219], v[178:181], v[38:41]
	v_mfma_f32_16x16x32_bf16 v[26:29], v[208:211], v[192:195], v[26:29]
	v_mfma_f32_16x16x32_bf16 v[22:25], v[216:219], v[192:195], v[22:25]
	v_mfma_f32_16x16x32_bf16 v[4:7], v[208:211], v[200:203], v[4:7]
	v_mfma_f32_16x16x32_bf16 v[0:3], v[216:219], v[200:203], v[0:3]
	v_mfma_f32_16x16x32_bf16 v[58:61], v[212:215], v[174:177], v[58:61]
	v_mfma_f32_16x16x32_bf16 v[54:57], v[220:223], v[174:177], v[54:57]
	v_mfma_f32_16x16x32_bf16 v[42:45], v[212:215], v[188:191], v[42:45]
	v_mfma_f32_16x16x32_bf16 v[38:41], v[220:223], v[188:191], v[38:41]
	v_mfma_f32_16x16x32_bf16 v[26:29], v[212:215], v[196:199], v[26:29]
	v_mfma_f32_16x16x32_bf16 v[22:25], v[220:223], v[196:199], v[22:25]
	v_mfma_f32_16x16x32_bf16 v[4:7], v[212:215], v[204:207], v[4:7]
	v_mfma_f32_16x16x32_bf16 v[0:3], v[220:223], v[204:207], v[0:3]
	s_setprio 0
	s_add_i32 s36, s36, 2
	s_add_u32 s12, s12, 0x100
	s_addc_u32 s13, s13, 0
	s_add_u32 s34, s34, 0x100
	s_addc_u32 s35, s35, 0
	s_cmp_gt_u32 s36, 13
	s_barrier
	s_cbranch_scc0 .LBB0_2754
	v_readlane_b32 s12, v251, 8
	s_cmp_eq_u32 s12, 0
	s_cbranch_scc1 .Llz_plain
	v_lshl_add_u32 v140, s10, 8, v21
	s_lshl_b32 s10, s11, 10
	v_readlane_b32 s14, v249, 4
	v_readlane_b32 s15, v249, 5
	v_readlane_b32 s13, v251, 6
	s_mov_b32 s16, 0x3fd744fd
	v_lshlrev_b32_e32 v141, 3, v140
	s_add_i32 s10, s10, s13
	s_add_i32 s12, s12, -1
	s_lshl_b32 s12, s12, 12
	v_add_u32_e32 v144, s10, v16
	v_readlane_b32 s72, v249, 38
	v_readlane_b32 s73, v249, 39
	v_readlane_b32 s74, v249, 40
	v_readlane_b32 s75, v249, 41
	v_readlane_b32 s76, v249, 0
	v_readlane_b32 s77, v249, 1
	v_lshl_add_u32 v140, v140, 12, v144
	s_add_u32 s72, s72, s12
	s_addc_u32 s73, s73, 0
	s_add_u32 s74, s74, s12
	s_addc_u32 s75, s75, 0
	s_add_u32 s76, s76, 0x2b234000
	s_addc_u32 s77, s77, 0
	s_add_u32 s56, s14, 0x0
	s_addc_u32 s57, s15, 0
	s_add_u32 s58, s14, 0x10000
	s_addc_u32 s59, s15, 0
	s_add_u32 s60, s14, 0x20000
	s_addc_u32 s61, s15, 0
	s_add_u32 s62, s14, 0x30000
	s_addc_u32 s63, s15, 0
	s_add_u32 s64, s14, 0x80000
	s_addc_u32 s65, s15, 0
	s_add_u32 s66, s14, 0x90000
	s_addc_u32 s67, s15, 0
	s_add_u32 s68, s14, 0xa0000
	s_addc_u32 s69, s15, 0
	s_add_u32 s70, s14, 0xb0000
	s_addc_u32 s71, s15, 0
	s_nop 1
	global_load_dwordx2 v[146:147], v141, s[76:77] offset:0
	global_load_dwordx2 v[148:149], v141, s[76:77] offset:128
	global_load_dwordx2 v[150:151], v141, s[76:77] offset:256
	global_load_dwordx2 v[154:155], v141, s[76:77] offset:384
	global_load_dwordx2 v[156:157], v141, s[76:77] offset:1024
	global_load_dwordx2 v[162:163], v141, s[76:77] offset:1152
	global_load_dwordx2 v[164:165], v141, s[76:77] offset:1280
	global_load_dwordx2 v[166:167], v141, s[76:77] offset:1408
	global_load_dwordx4 v[168:171], v144, s[72:73]
	global_load_dwordx4 v[172:175], v144, s[74:75]
	global_load_dwordx4 v[176:179], v144, s[72:73] offset:64
	global_load_dwordx4 v[186:189], v144, s[74:75] offset:64
	global_load_dwordx4 v[190:193], v140, s[56:57]
	global_load_dwordx4 v[194:197], v140, s[58:59]
	global_load_dwordx4 v[198:201], v140, s[60:61]
	global_load_dwordx4 v[204:207], v140, s[62:63]
	global_load_dwordx4 v[208:211], v140, s[64:65]
	global_load_dwordx4 v[212:215], v140, s[66:67]
	global_load_dwordx4 v[216:219], v140, s[68:69]
	global_load_dwordx4 v[220:223], v140, s[70:71]
	global_load_dwordx4 v[224:227], v140, s[56:57] offset:64
	global_load_dwordx4 v[228:231], v140, s[58:59] offset:64
	global_load_dwordx4 v[232:235], v140, s[60:61] offset:64
	global_load_dwordx4 v[236:239], v140, s[62:63] offset:64
	global_load_dwordx4 v[240:243], v140, s[64:65] offset:64
	global_load_dwordx4 v[244:247], v140, s[66:67] offset:64
	s_waitcnt vmcnt(13)
; DI bf16x4 pack4(float a, float b, float c, float d) { u32x2v u; u.x = pk2(a, b); u.y = pk2(c, d); return __builtin_bit_cast(bf16x4, u); }
; DI void ln_rows2(const float* s0, const float* s1, const float* g, const float* b, float* d0, bf16_t* db0, float* d1, bf16_t* db1, int lane) {
;     ...
;     o.x = (v0[i].x - mu0) * r0 * gg.x + bb.x; o.y = (v0[i].y - mu0) * r0 * gg.y + bb.y; o.z = (v0[i].z - mu0) * r0 * gg.z + bb.z; o.w = (v0[i].w - mu0) * r0 * gg.w + bb.w;
;     reinterpret_cast<float4*>(d0)[lane + 64 * i] = o; st4(db0 + 4 * (lane + 64 * i), pack4(o.x, o.y, o.z, o.w));
;     o.x = (v1[i].x - mu1) * r1 * gg.x + bb.x; o.y = (v1[i].y - mu1) * r1 * gg.y + bb.y; o.z = (v1[i].z - mu1) * r1 * gg.z + bb.z; o.w = (v1[i].w - mu1) * r1 * gg.w + bb.w;
;     reinterpret_cast<float4*>(d1)[lane + 64 * i] = o; st4(db1 + 4 * (lane + 64 * i), pack4(o.x, o.y, o.z, o.w));
;   DI void operator()(const f32x4 (&acc)[2][2][4][2], const pg8::Unit& u, int wr, int wc, int fr, int fq) const {
;     ...
;               f32x4 x = *reinterpret_cast<const f32x4*>(p.out + idx);
;               x = x * ALPHA + a;
;               *reinterpret_cast<f32x4*>(p.out + idx) = x;
	v_pk_add_f32 v[190:191], v[190:191], v[146:147] op_sel_hi:[1,0] neg_lo:[0,1] neg_hi:[0,1]
	v_pk_add_f32 v[192:193], v[192:193], v[146:147] op_sel_hi:[1,0] neg_lo:[0,1] neg_hi:[0,1]
	v_pk_mul_f32 v[190:191], v[190:191], v[146:147] op_sel:[0,1] op_sel_hi:[1,1]
	v_pk_mul_f32 v[192:193], v[192:193], v[146:147] op_sel:[0,1] op_sel_hi:[1,1]
	v_pk_fma_f32 v[190:191], v[190:191], v[168:169], v[172:173]
	v_pk_fma_f32 v[192:193], v[192:193], v[170:171], v[174:175]
	v_pk_fma_f32 v[130:131], v[190:191], s[16:17], v[130:131] op_sel_hi:[1,0,1]
	v_pk_fma_f32 v[132:133], v[192:193], s[16:17], v[132:133] op_sel_hi:[1,0,1]
	global_store_dwordx4 v140, v[130:133], s[56:57]
	global_load_dwordx4 v[190:193], v140, s[68:69] offset:64
	s_waitcnt vmcnt(14)
	v_pk_add_f32 v[194:195], v[194:195], v[148:149] op_sel_hi:[1,0] neg_lo:[0,1] neg_hi:[0,1]
	v_pk_add_f32 v[196:197], v[196:197], v[148:149] op_sel_hi:[1,0] neg_lo:[0,1] neg_hi:[0,1]
	v_pk_mul_f32 v[194:195], v[194:195], v[148:149] op_sel:[0,1] op_sel_hi:[1,1]
	v_pk_mul_f32 v[196:197], v[196:197], v[148:149] op_sel:[0,1] op_sel_hi:[1,1]
	v_pk_fma_f32 v[194:195], v[194:195], v[168:169], v[172:173]
	v_pk_fma_f32 v[196:197], v[196:197], v[170:171], v[174:175]
	v_pk_fma_f32 v[114:115], v[194:195], s[16:17], v[114:115] op_sel_hi:[1,0,1]
	v_pk_fma_f32 v[116:117], v[196:197], s[16:17], v[116:117] op_sel_hi:[1,0,1]
	global_store_dwordx4 v140, v[114:117], s[58:59]
	global_load_dwordx4 v[194:197], v140, s[70:71] offset:64
	s_waitcnt vmcnt(15)
	v_pk_add_f32 v[198:199], v[198:199], v[150:151] op_sel_hi:[1,0] neg_lo:[0,1] neg_hi:[0,1]
	v_pk_add_f32 v[200:201], v[200:201], v[150:151] op_sel_hi:[1,0] neg_lo:[0,1] neg_hi:[0,1]
	v_pk_mul_f32 v[198:199], v[198:199], v[150:151] op_sel:[0,1] op_sel_hi:[1,1]
	v_pk_mul_f32 v[200:201], v[200:201], v[150:151] op_sel:[0,1] op_sel_hi:[1,1]
	v_pk_fma_f32 v[198:199], v[198:199], v[168:169], v[172:173]
	v_pk_fma_f32 v[200:201], v[200:201], v[170:171], v[174:175]
	v_pk_fma_f32 v[98:99], v[198:199], s[16:17], v[98:99] op_sel_hi:[1,0,1]
	v_pk_fma_f32 v[100:101], v[200:201], s[16:17], v[100:101] op_sel_hi:[1,0,1]
	global_store_dwordx4 v140, v[98:101], s[60:61]
	global_load_dwordx4 v[198:201], v140, s[56:57] offset:512
	s_waitcnt vmcnt(16)
	v_pk_add_f32 v[204:205], v[204:205], v[154:155] op_sel_hi:[1,0] neg_lo:[0,1] neg_hi:[0,1]
	v_pk_add_f32 v[206:207], v[206:207], v[154:155] op_sel_hi:[1,0] neg_lo:[0,1] neg_hi:[0,1]
	v_pk_mul_f32 v[204:205], v[204:205], v[154:155] op_sel:[0,1] op_sel_hi:[1,1]
	v_pk_mul_f32 v[206:207], v[206:207], v[154:155] op_sel:[0,1] op_sel_hi:[1,1]
	v_pk_fma_f32 v[204:205], v[204:205], v[168:169], v[172:173]
	v_pk_fma_f32 v[206:207], v[206:207], v[170:171], v[174:175]
	v_pk_fma_f32 v[82:83], v[204:205], s[16:17], v[82:83] op_sel_hi:[1,0,1]
	v_pk_fma_f32 v[84:85], v[206:207], s[16:17], v[84:85] op_sel_hi:[1,0,1]
	global_store_dwordx4 v140, v[82:85], s[62:63]
	global_load_dwordx4 v[204:207], v140, s[58:59] offset:512
	s_waitcnt vmcnt(17)
	v_pk_add_f32 v[208:209], v[208:209], v[156:157] op_sel_hi:[1,0] neg_lo:[0,1] neg_hi:[0,1]
	v_pk_add_f32 v[210:211], v[210:211], v[156:157] op_sel_hi:[1,0] neg_lo:[0,1] neg_hi:[0,1]
	v_pk_mul_f32 v[208:209], v[208:209], v[156:157] op_sel:[0,1] op_sel_hi:[1,1]
	v_pk_mul_f32 v[210:211], v[210:211], v[156:157] op_sel:[0,1] op_sel_hi:[1,1]
	v_pk_fma_f32 v[208:209], v[208:209], v[168:169], v[172:173]
	v_pk_fma_f32 v[210:211], v[210:211], v[170:171], v[174:175]
	v_pk_fma_f32 v[66:67], v[208:209], s[16:17], v[66:67] op_sel_hi:[1,0,1]
	v_pk_fma_f32 v[68:69], v[210:211], s[16:17], v[68:69] op_sel_hi:[1,0,1]
	global_store_dwordx4 v140, v[66:69], s[64:65]
	global_load_dwordx4 v[208:211], v140, s[60:61] offset:512
	s_waitcnt vmcnt(18)
	v_pk_add_f32 v[212:213], v[212:213], v[162:163] op_sel_hi:[1,0] neg_lo:[0,1] neg_hi:[0,1]
	v_pk_add_f32 v[214:215], v[214:215], v[162:163] op_sel_hi:[1,0] neg_lo:[0,1] neg_hi:[0,1]
	v_pk_mul_f32 v[212:213], v[212:213], v[162:163] op_sel:[0,1] op_sel_hi:[1,1]
	v_pk_mul_f32 v[214:215], v[214:215], v[162:163] op_sel:[0,1] op_sel_hi:[1,1]
	v_pk_fma_f32 v[212:213], v[212:213], v[168:169], v[172:173]
	v_pk_fma_f32 v[214:215], v[214:215], v[170:171], v[174:175]
	v_pk_fma_f32 v[50:51], v[212:213], s[16:17], v[50:51] op_sel_hi:[1,0,1]
	v_pk_fma_f32 v[52:53], v[214:215], s[16:17], v[52:53] op_sel_hi:[1,0,1]
	global_store_dwordx4 v140, v[50:53], s[66:67]
	global_load_dwordx4 v[212:215], v140, s[62:63] offset:512
	s_waitcnt vmcnt(19)
	v_pk_add_f32 v[216:217], v[216:217], v[164:165] op_sel_hi:[1,0] neg_lo:[0,1] neg_hi:[0,1]
	v_pk_add_f32 v[218:219], v[218:219], v[164:165] op_sel_hi:[1,0] neg_lo:[0,1] neg_hi:[0,1]
	v_pk_mul_f32 v[216:217], v[216:217], v[164:165] op_sel:[0,1] op_sel_hi:[1,1]
	v_pk_mul_f32 v[218:219], v[218:219], v[164:165] op_sel:[0,1] op_sel_hi:[1,1]
	v_pk_fma_f32 v[216:217], v[216:217], v[168:169], v[172:173]
	v_pk_fma_f32 v[218:219], v[218:219], v[170:171], v[174:175]
	v_pk_fma_f32 v[34:35], v[216:217], s[16:17], v[34:35] op_sel_hi:[1,0,1]
	v_pk_fma_f32 v[36:37], v[218:219], s[16:17], v[36:37] op_sel_hi:[1,0,1]
	global_store_dwordx4 v140, v[34:37], s[68:69]
	global_load_dwordx4 v[216:219], v140, s[64:65] offset:512
	s_waitcnt vmcnt(20)
	v_pk_add_f32 v[220:221], v[220:221], v[166:167] op_sel_hi:[1,0] neg_lo:[0,1] neg_hi:[0,1]
	v_pk_add_f32 v[222:223], v[222:223], v[166:167] op_sel_hi:[1,0] neg_lo:[0,1] neg_hi:[0,1]
	v_pk_mul_f32 v[220:221], v[220:221], v[166:167] op_sel:[0,1] op_sel_hi:[1,1]
	v_pk_mul_f32 v[222:223], v[222:223], v[166:167] op_sel:[0,1] op_sel_hi:[1,1]
	v_pk_fma_f32 v[220:221], v[220:221], v[168:169], v[172:173]
	v_pk_fma_f32 v[222:223], v[222:223], v[170:171], v[174:175]
	v_pk_fma_f32 v[12:13], v[220:221], s[16:17], v[12:13] op_sel_hi:[1,0,1]
	v_pk_fma_f32 v[14:15], v[222:223], s[16:17], v[14:15] op_sel_hi:[1,0,1]
	global_store_dwordx4 v140, v[12:15], s[70:71]
	global_load_dwordx4 v[220:223], v140, s[66:67] offset:512
	global_load_dwordx4 v[168:171], v144, s[72:73] offset:512
	global_load_dwordx4 v[172:175], v144, s[74:75] offset:512
	s_waitcnt vmcnt(23)
; DI bf16x4 pack4(float a, float b, float c, float d) { u32x2v u; u.x = pk2(a, b); u.y = pk2(c, d); return __builtin_bit_cast(bf16x4, u); }
; DI void ln_rows2(const float* s0, const float* s1, const float* g, const float* b, float* d0, bf16_t* db0, float* d1, bf16_t* db1, int lane) {
;     ...
;     o.x = (v0[i].x - mu0) * r0 * gg.x + bb.x; o.y = (v0[i].y - mu0) * r0 * gg.y + bb.y; o.z = (v0[i].z - mu0) * r0 * gg.z + bb.z; o.w = (v0[i].w - mu0) * r0 * gg.w + bb.w;
;     reinterpret_cast<float4*>(d0)[lane + 64 * i] = o; st4(db0 + 4 * (lane + 64 * i), pack4(o.x, o.y, o.z, o.w));
;     o.x = (v1[i].x - mu1) * r1 * gg.x + bb.x; o.y = (v1[i].y - mu1) * r1 * gg.y + bb.y; o.z = (v1[i].z - mu1) * r1 * gg.z + bb.z; o.w = (v1[i].w - mu1) * r1 * gg.w + bb.w;
;     reinterpret_cast<float4*>(d1)[lane + 64 * i] = o; st4(db1 + 4 * (lane + 64 * i), pack4(o.x, o.y, o.z, o.w));
;   DI void operator()(const f32x4 (&acc)[2][2][4][2], const pg8::Unit& u, int wr, int wc, int fr, int fq) const {
;     ...
;               f32x4 x = *reinterpret_cast<const f32x4*>(p.out + idx);
;               x = x * ALPHA + a;
;               *reinterpret_cast<f32x4*>(p.out + idx) = x;
	v_pk_add_f32 v[224:225], v[224:225], v[146:147] op_sel_hi:[1,0] neg_lo:[0,1] neg_hi:[0,1]
	v_pk_add_f32 v[226:227], v[226:227], v[146:147] op_sel_hi:[1,0] neg_lo:[0,1] neg_hi:[0,1]
	v_pk_mul_f32 v[224:225], v[224:225], v[146:147] op_sel:[0,1] op_sel_hi:[1,1]
	v_pk_mul_f32 v[226:227], v[226:227], v[146:147] op_sel:[0,1] op_sel_hi:[1,1]
	v_pk_fma_f32 v[224:225], v[224:225], v[176:177], v[186:187]
	v_pk_fma_f32 v[226:227], v[226:227], v[178:179], v[188:189]
	v_pk_fma_f32 v[126:127], v[224:225], s[16:17], v[126:127] op_sel_hi:[1,0,1]
	v_pk_fma_f32 v[128:129], v[226:227], s[16:17], v[128:129] op_sel_hi:[1,0,1]
	global_store_dwordx4 v140, v[126:129], s[56:57] offset:64
	global_load_dwordx4 v[224:227], v140, s[68:69] offset:512
	s_waitcnt vmcnt(24)
	v_pk_add_f32 v[228:229], v[228:229], v[148:149] op_sel_hi:[1,0] neg_lo:[0,1] neg_hi:[0,1]
	v_pk_add_f32 v[230:231], v[230:231], v[148:149] op_sel_hi:[1,0] neg_lo:[0,1] neg_hi:[0,1]
	v_pk_mul_f32 v[228:229], v[228:229], v[148:149] op_sel:[0,1] op_sel_hi:[1,1]
	v_pk_mul_f32 v[230:231], v[230:231], v[148:149] op_sel:[0,1] op_sel_hi:[1,1]
	v_pk_fma_f32 v[228:229], v[228:229], v[176:177], v[186:187]
	v_pk_fma_f32 v[230:231], v[230:231], v[178:179], v[188:189]
	v_pk_fma_f32 v[110:111], v[228:229], s[16:17], v[110:111] op_sel_hi:[1,0,1]
	v_pk_fma_f32 v[112:113], v[230:231], s[16:17], v[112:113] op_sel_hi:[1,0,1]
	global_store_dwordx4 v140, v[110:113], s[58:59] offset:64
	global_load_dwordx4 v[228:231], v140, s[70:71] offset:512
	s_waitcnt vmcnt(25)
	v_pk_add_f32 v[232:233], v[232:233], v[150:151] op_sel_hi:[1,0] neg_lo:[0,1] neg_hi:[0,1]
	v_pk_add_f32 v[234:235], v[234:235], v[150:151] op_sel_hi:[1,0] neg_lo:[0,1] neg_hi:[0,1]
	v_pk_mul_f32 v[232:233], v[232:233], v[150:151] op_sel:[0,1] op_sel_hi:[1,1]
	v_pk_mul_f32 v[234:235], v[234:235], v[150:151] op_sel:[0,1] op_sel_hi:[1,1]
	v_pk_fma_f32 v[232:233], v[232:233], v[176:177], v[186:187]
	v_pk_fma_f32 v[234:235], v[234:235], v[178:179], v[188:189]
	v_pk_fma_f32 v[94:95], v[232:233], s[16:17], v[94:95] op_sel_hi:[1,0,1]
	v_pk_fma_f32 v[96:97], v[234:235], s[16:17], v[96:97] op_sel_hi:[1,0,1]
	global_store_dwordx4 v140, v[94:97], s[60:61] offset:64
	global_load_dwordx4 v[232:235], v140, s[56:57] offset:576
	s_waitcnt vmcnt(26)
	v_pk_add_f32 v[236:237], v[236:237], v[154:155] op_sel_hi:[1,0] neg_lo:[0,1] neg_hi:[0,1]
	v_pk_add_f32 v[238:239], v[238:239], v[154:155] op_sel_hi:[1,0] neg_lo:[0,1] neg_hi:[0,1]
	v_pk_mul_f32 v[236:237], v[236:237], v[154:155] op_sel:[0,1] op_sel_hi:[1,1]
	v_pk_mul_f32 v[238:239], v[238:239], v[154:155] op_sel:[0,1] op_sel_hi:[1,1]
	v_pk_fma_f32 v[236:237], v[236:237], v[176:177], v[186:187]
	v_pk_fma_f32 v[238:239], v[238:239], v[178:179], v[188:189]
	v_pk_fma_f32 v[78:79], v[236:237], s[16:17], v[78:79] op_sel_hi:[1,0,1]
	v_pk_fma_f32 v[80:81], v[238:239], s[16:17], v[80:81] op_sel_hi:[1,0,1]
	global_store_dwordx4 v140, v[78:81], s[62:63] offset:64
	global_load_dwordx4 v[236:239], v140, s[58:59] offset:576
	s_waitcnt vmcnt(27)
	v_pk_add_f32 v[240:241], v[240:241], v[156:157] op_sel_hi:[1,0] neg_lo:[0,1] neg_hi:[0,1]
	v_pk_add_f32 v[242:243], v[242:243], v[156:157] op_sel_hi:[1,0] neg_lo:[0,1] neg_hi:[0,1]
	v_pk_mul_f32 v[240:241], v[240:241], v[156:157] op_sel:[0,1] op_sel_hi:[1,1]
	v_pk_mul_f32 v[242:243], v[242:243], v[156:157] op_sel:[0,1] op_sel_hi:[1,1]
	v_pk_fma_f32 v[240:241], v[240:241], v[176:177], v[186:187]
	v_pk_fma_f32 v[242:243], v[242:243], v[178:179], v[188:189]
	v_pk_fma_f32 v[62:63], v[240:241], s[16:17], v[62:63] op_sel_hi:[1,0,1]
	v_pk_fma_f32 v[64:65], v[242:243], s[16:17], v[64:65] op_sel_hi:[1,0,1]
	global_store_dwordx4 v140, v[62:65], s[64:65] offset:64
	global_load_dwordx4 v[240:243], v140, s[60:61] offset:576
	s_waitcnt vmcnt(28)
	v_pk_add_f32 v[244:245], v[244:245], v[162:163] op_sel_hi:[1,0] neg_lo:[0,1] neg_hi:[0,1]
	v_pk_add_f32 v[246:247], v[246:247], v[162:163] op_sel_hi:[1,0] neg_lo:[0,1] neg_hi:[0,1]
	v_pk_mul_f32 v[244:245], v[244:245], v[162:163] op_sel:[0,1] op_sel_hi:[1,1]
	v_pk_mul_f32 v[246:247], v[246:247], v[162:163] op_sel:[0,1] op_sel_hi:[1,1]
	v_pk_fma_f32 v[244:245], v[244:245], v[176:177], v[186:187]
	v_pk_fma_f32 v[246:247], v[246:247], v[178:179], v[188:189]
	v_pk_fma_f32 v[46:47], v[244:245], s[16:17], v[46:47] op_sel_hi:[1,0,1]
	v_pk_fma_f32 v[48:49], v[246:247], s[16:17], v[48:49] op_sel_hi:[1,0,1]
	global_store_dwordx4 v140, v[46:49], s[66:67] offset:64
	global_load_dwordx4 v[244:247], v140, s[62:63] offset:576
	s_waitcnt vmcnt(28)
	v_pk_add_f32 v[190:191], v[190:191], v[164:165] op_sel_hi:[1,0] neg_lo:[0,1] neg_hi:[0,1]
	v_pk_add_f32 v[192:193], v[192:193], v[164:165] op_sel_hi:[1,0] neg_lo:[0,1] neg_hi:[0,1]
	v_pk_mul_f32 v[190:191], v[190:191], v[164:165] op_sel:[0,1] op_sel_hi:[1,1]
	v_pk_mul_f32 v[192:193], v[192:193], v[164:165] op_sel:[0,1] op_sel_hi:[1,1]
	v_pk_fma_f32 v[190:191], v[190:191], v[176:177], v[186:187]
	v_pk_fma_f32 v[192:193], v[192:193], v[178:179], v[188:189]
	v_pk_fma_f32 v[30:31], v[190:191], s[16:17], v[30:31] op_sel_hi:[1,0,1]
	v_pk_fma_f32 v[32:33], v[192:193], s[16:17], v[32:33] op_sel_hi:[1,0,1]
	global_store_dwordx4 v140, v[30:33], s[68:69] offset:64
	global_load_dwordx4 v[190:193], v140, s[64:65] offset:576
	s_waitcnt vmcnt(28)
; DI bf16x4 pack4(float a, float b, float c, float d) { u32x2v u; u.x = pk2(a, b); u.y = pk2(c, d); return __builtin_bit_cast(bf16x4, u); }
; DI void ln_rows2(const float* s0, const float* s1, const float* g, const float* b, float* d0, bf16_t* db0, float* d1, bf16_t* db1, int lane) {
;     ...
;     o.x = (v0[i].x - mu0) * r0 * gg.x + bb.x; o.y = (v0[i].y - mu0) * r0 * gg.y + bb.y; o.z = (v0[i].z - mu0) * r0 * gg.z + bb.z; o.w = (v0[i].w - mu0) * r0 * gg.w + bb.w;
;     reinterpret_cast<float4*>(d0)[lane + 64 * i] = o; st4(db0 + 4 * (lane + 64 * i), pack4(o.x, o.y, o.z, o.w));
;     o.x = (v1[i].x - mu1) * r1 * gg.x + bb.x; o.y = (v1[i].y - mu1) * r1 * gg.y + bb.y; o.z = (v1[i].z - mu1) * r1 * gg.z + bb.z; o.w = (v1[i].w - mu1) * r1 * gg.w + bb.w;
;     reinterpret_cast<float4*>(d1)[lane + 64 * i] = o; st4(db1 + 4 * (lane + 64 * i), pack4(o.x, o.y, o.z, o.w));
;   DI void operator()(const f32x4 (&acc)[2][2][4][2], const pg8::Unit& u, int wr, int wc, int fr, int fq) const {
;     ...
;               f32x4 x = *reinterpret_cast<const f32x4*>(p.out + idx);
;               x = x * ALPHA + a;
;               *reinterpret_cast<f32x4*>(p.out + idx) = x;
	v_pk_add_f32 v[194:195], v[194:195], v[166:167] op_sel_hi:[1,0] neg_lo:[0,1] neg_hi:[0,1]
	v_pk_add_f32 v[196:197], v[196:197], v[166:167] op_sel_hi:[1,0] neg_lo:[0,1] neg_hi:[0,1]
	v_pk_mul_f32 v[194:195], v[194:195], v[166:167] op_sel:[0,1] op_sel_hi:[1,1]
	v_pk_mul_f32 v[196:197], v[196:197], v[166:167] op_sel:[0,1] op_sel_hi:[1,1]
	v_pk_fma_f32 v[194:195], v[194:195], v[176:177], v[186:187]
	v_pk_fma_f32 v[196:197], v[196:197], v[178:179], v[188:189]
	v_pk_fma_f32 v[8:9], v[194:195], s[16:17], v[8:9] op_sel_hi:[1,0,1]
	v_pk_fma_f32 v[10:11], v[196:197], s[16:17], v[10:11] op_sel_hi:[1,0,1]
	global_store_dwordx4 v140, v[8:11], s[70:71] offset:64
	global_load_dwordx4 v[194:197], v140, s[66:67] offset:576
	global_load_dwordx4 v[176:179], v144, s[72:73] offset:576
	global_load_dwordx4 v[186:189], v144, s[74:75] offset:576
	s_waitcnt vmcnt(18)
	v_pk_add_f32 v[198:199], v[198:199], v[146:147] op_sel_hi:[1,0] neg_lo:[0,1] neg_hi:[0,1]
	v_pk_add_f32 v[200:201], v[200:201], v[146:147] op_sel_hi:[1,0] neg_lo:[0,1] neg_hi:[0,1]
	v_pk_mul_f32 v[198:199], v[198:199], v[146:147] op_sel:[0,1] op_sel_hi:[1,1]
	v_pk_mul_f32 v[200:201], v[200:201], v[146:147] op_sel:[0,1] op_sel_hi:[1,1]
	v_pk_fma_f32 v[198:199], v[198:199], v[168:169], v[172:173]
	v_pk_fma_f32 v[200:201], v[200:201], v[170:171], v[174:175]
	v_pk_fma_f32 v[122:123], v[198:199], s[16:17], v[122:123] op_sel_hi:[1,0,1]
	v_pk_fma_f32 v[124:125], v[200:201], s[16:17], v[124:125] op_sel_hi:[1,0,1]
	global_store_dwordx4 v140, v[122:125], s[56:57] offset:512
	global_load_dwordx4 v[198:201], v140, s[68:69] offset:576
	s_waitcnt vmcnt(20)
	v_pk_add_f32 v[204:205], v[204:205], v[148:149] op_sel_hi:[1,0] neg_lo:[0,1] neg_hi:[0,1]
	v_pk_add_f32 v[206:207], v[206:207], v[148:149] op_sel_hi:[1,0] neg_lo:[0,1] neg_hi:[0,1]
	v_pk_mul_f32 v[204:205], v[204:205], v[148:149] op_sel:[0,1] op_sel_hi:[1,1]
	v_pk_mul_f32 v[206:207], v[206:207], v[148:149] op_sel:[0,1] op_sel_hi:[1,1]
	v_pk_fma_f32 v[204:205], v[204:205], v[168:169], v[172:173]
	v_pk_fma_f32 v[206:207], v[206:207], v[170:171], v[174:175]
	v_pk_fma_f32 v[106:107], v[204:205], s[16:17], v[106:107] op_sel_hi:[1,0,1]
	v_pk_fma_f32 v[108:109], v[206:207], s[16:17], v[108:109] op_sel_hi:[1,0,1]
	global_store_dwordx4 v140, v[106:109], s[58:59] offset:512
	global_load_dwordx4 v[204:207], v140, s[70:71] offset:576
	s_waitcnt vmcnt(22)
	v_pk_add_f32 v[208:209], v[208:209], v[150:151] op_sel_hi:[1,0] neg_lo:[0,1] neg_hi:[0,1]
	v_pk_add_f32 v[210:211], v[210:211], v[150:151] op_sel_hi:[1,0] neg_lo:[0,1] neg_hi:[0,1]
	v_pk_mul_f32 v[208:209], v[208:209], v[150:151] op_sel:[0,1] op_sel_hi:[1,1]
	v_pk_mul_f32 v[210:211], v[210:211], v[150:151] op_sel:[0,1] op_sel_hi:[1,1]
	v_pk_fma_f32 v[208:209], v[208:209], v[168:169], v[172:173]
	v_pk_fma_f32 v[210:211], v[210:211], v[170:171], v[174:175]
	v_pk_fma_f32 v[90:91], v[208:209], s[16:17], v[90:91] op_sel_hi:[1,0,1]
	v_pk_fma_f32 v[92:93], v[210:211], s[16:17], v[92:93] op_sel_hi:[1,0,1]
	global_store_dwordx4 v140, v[90:93], s[60:61] offset:512
	s_waitcnt vmcnt(23)
	v_pk_add_f32 v[212:213], v[212:213], v[154:155] op_sel_hi:[1,0] neg_lo:[0,1] neg_hi:[0,1]
	v_pk_add_f32 v[214:215], v[214:215], v[154:155] op_sel_hi:[1,0] neg_lo:[0,1] neg_hi:[0,1]
	v_pk_mul_f32 v[212:213], v[212:213], v[154:155] op_sel:[0,1] op_sel_hi:[1,1]
	v_pk_mul_f32 v[214:215], v[214:215], v[154:155] op_sel:[0,1] op_sel_hi:[1,1]
	v_pk_fma_f32 v[212:213], v[212:213], v[168:169], v[172:173]
	v_pk_fma_f32 v[214:215], v[214:215], v[170:171], v[174:175]
	v_pk_fma_f32 v[74:75], v[212:213], s[16:17], v[74:75] op_sel_hi:[1,0,1]
	v_pk_fma_f32 v[76:77], v[214:215], s[16:17], v[76:77] op_sel_hi:[1,0,1]
	global_store_dwordx4 v140, v[74:77], s[62:63] offset:512
	s_waitcnt vmcnt(24)
	v_pk_add_f32 v[216:217], v[216:217], v[156:157] op_sel_hi:[1,0] neg_lo:[0,1] neg_hi:[0,1]
	v_pk_add_f32 v[218:219], v[218:219], v[156:157] op_sel_hi:[1,0] neg_lo:[0,1] neg_hi:[0,1]
	v_pk_mul_f32 v[216:217], v[216:217], v[156:157] op_sel:[0,1] op_sel_hi:[1,1]
	v_pk_mul_f32 v[218:219], v[218:219], v[156:157] op_sel:[0,1] op_sel_hi:[1,1]
	v_pk_fma_f32 v[216:217], v[216:217], v[168:169], v[172:173]
	v_pk_fma_f32 v[218:219], v[218:219], v[170:171], v[174:175]
	v_pk_fma_f32 v[58:59], v[216:217], s[16:17], v[58:59] op_sel_hi:[1,0,1]
	v_pk_fma_f32 v[60:61], v[218:219], s[16:17], v[60:61] op_sel_hi:[1,0,1]
	global_store_dwordx4 v140, v[58:61], s[64:65] offset:512
	s_waitcnt vmcnt(25)
	v_pk_add_f32 v[220:221], v[220:221], v[162:163] op_sel_hi:[1,0] neg_lo:[0,1] neg_hi:[0,1]
	v_pk_add_f32 v[222:223], v[222:223], v[162:163] op_sel_hi:[1,0] neg_lo:[0,1] neg_hi:[0,1]
	v_pk_mul_f32 v[220:221], v[220:221], v[162:163] op_sel:[0,1] op_sel_hi:[1,1]
	v_pk_mul_f32 v[222:223], v[222:223], v[162:163] op_sel:[0,1] op_sel_hi:[1,1]
	v_pk_fma_f32 v[220:221], v[220:221], v[168:169], v[172:173]
	v_pk_fma_f32 v[222:223], v[222:223], v[170:171], v[174:175]
	v_pk_fma_f32 v[42:43], v[220:221], s[16:17], v[42:43] op_sel_hi:[1,0,1]
	v_pk_fma_f32 v[44:45], v[222:223], s[16:17], v[44:45] op_sel_hi:[1,0,1]
	global_store_dwordx4 v140, v[42:45], s[66:67] offset:512
	s_waitcnt vmcnt(24)
	v_pk_add_f32 v[224:225], v[224:225], v[164:165] op_sel_hi:[1,0] neg_lo:[0,1] neg_hi:[0,1]
	v_pk_add_f32 v[226:227], v[226:227], v[164:165] op_sel_hi:[1,0] neg_lo:[0,1] neg_hi:[0,1]
	v_pk_mul_f32 v[224:225], v[224:225], v[164:165] op_sel:[0,1] op_sel_hi:[1,1]
	v_pk_mul_f32 v[226:227], v[226:227], v[164:165] op_sel:[0,1] op_sel_hi:[1,1]
	v_pk_fma_f32 v[224:225], v[224:225], v[168:169], v[172:173]
	v_pk_fma_f32 v[226:227], v[226:227], v[170:171], v[174:175]
	v_pk_fma_f32 v[26:27], v[224:225], s[16:17], v[26:27] op_sel_hi:[1,0,1]
	v_pk_fma_f32 v[28:29], v[226:227], s[16:17], v[28:29] op_sel_hi:[1,0,1]
	global_store_dwordx4 v140, v[26:29], s[68:69] offset:512
	s_waitcnt vmcnt(23)
; DI bf16x4 pack4(float a, float b, float c, float d) { u32x2v u; u.x = pk2(a, b); u.y = pk2(c, d); return __builtin_bit_cast(bf16x4, u); }
; DI void ln_rows2(const float* s0, const float* s1, const float* g, const float* b, float* d0, bf16_t* db0, float* d1, bf16_t* db1, int lane) {
;     ...
;     o.x = (v0[i].x - mu0) * r0 * gg.x + bb.x; o.y = (v0[i].y - mu0) * r0 * gg.y + bb.y; o.z = (v0[i].z - mu0) * r0 * gg.z + bb.z; o.w = (v0[i].w - mu0) * r0 * gg.w + bb.w;
;     reinterpret_cast<float4*>(d0)[lane + 64 * i] = o; st4(db0 + 4 * (lane + 64 * i), pack4(o.x, o.y, o.z, o.w));
;     o.x = (v1[i].x - mu1) * r1 * gg.x + bb.x; o.y = (v1[i].y - mu1) * r1 * gg.y + bb.y; o.z = (v1[i].z - mu1) * r1 * gg.z + bb.z; o.w = (v1[i].w - mu1) * r1 * gg.w + bb.w;
;     reinterpret_cast<float4*>(d1)[lane + 64 * i] = o; st4(db1 + 4 * (lane + 64 * i), pack4(o.x, o.y, o.z, o.w));
;   DI void operator()(const f32x4 (&acc)[2][2][4][2], const pg8::Unit& u, int wr, int wc, int fr, int fq) const {
;     ...
;               f32x4 x = *reinterpret_cast<const f32x4*>(p.out + idx);
;               x = x * ALPHA + a;
;               *reinterpret_cast<f32x4*>(p.out + idx) = x;
	v_pk_add_f32 v[228:229], v[228:229], v[166:167] op_sel_hi:[1,0] neg_lo:[0,1] neg_hi:[0,1]
	v_pk_add_f32 v[230:231], v[230:231], v[166:167] op_sel_hi:[1,0] neg_lo:[0,1] neg_hi:[0,1]
	v_pk_mul_f32 v[228:229], v[228:229], v[166:167] op_sel:[0,1] op_sel_hi:[1,1]
	v_pk_mul_f32 v[230:231], v[230:231], v[166:167] op_sel:[0,1] op_sel_hi:[1,1]
	v_pk_fma_f32 v[228:229], v[228:229], v[168:169], v[172:173]
	v_pk_fma_f32 v[230:231], v[230:231], v[170:171], v[174:175]
	v_pk_fma_f32 v[4:5], v[228:229], s[16:17], v[4:5] op_sel_hi:[1,0,1]
	v_pk_fma_f32 v[6:7], v[230:231], s[16:17], v[6:7] op_sel_hi:[1,0,1]
	global_store_dwordx4 v140, v[4:7], s[70:71] offset:512
	s_waitcnt vmcnt(10)
	v_pk_add_f32 v[232:233], v[232:233], v[146:147] op_sel_hi:[1,0] neg_lo:[0,1] neg_hi:[0,1]
	v_pk_add_f32 v[234:235], v[234:235], v[146:147] op_sel_hi:[1,0] neg_lo:[0,1] neg_hi:[0,1]
	v_pk_mul_f32 v[232:233], v[232:233], v[146:147] op_sel:[0,1] op_sel_hi:[1,1]
	v_pk_mul_f32 v[234:235], v[234:235], v[146:147] op_sel:[0,1] op_sel_hi:[1,1]
	v_pk_fma_f32 v[232:233], v[232:233], v[176:177], v[186:187]
	v_pk_fma_f32 v[234:235], v[234:235], v[178:179], v[188:189]
	v_pk_fma_f32 v[118:119], v[232:233], s[16:17], v[118:119] op_sel_hi:[1,0,1]
	v_pk_fma_f32 v[120:121], v[234:235], s[16:17], v[120:121] op_sel_hi:[1,0,1]
	global_store_dwordx4 v140, v[118:121], s[56:57] offset:576
	s_waitcnt vmcnt(11)
	v_pk_add_f32 v[236:237], v[236:237], v[148:149] op_sel_hi:[1,0] neg_lo:[0,1] neg_hi:[0,1]
	v_pk_add_f32 v[238:239], v[238:239], v[148:149] op_sel_hi:[1,0] neg_lo:[0,1] neg_hi:[0,1]
	v_pk_mul_f32 v[236:237], v[236:237], v[148:149] op_sel:[0,1] op_sel_hi:[1,1]
	v_pk_mul_f32 v[238:239], v[238:239], v[148:149] op_sel:[0,1] op_sel_hi:[1,1]
	v_pk_fma_f32 v[236:237], v[236:237], v[176:177], v[186:187]
	v_pk_fma_f32 v[238:239], v[238:239], v[178:179], v[188:189]
	v_pk_fma_f32 v[102:103], v[236:237], s[16:17], v[102:103] op_sel_hi:[1,0,1]
	v_pk_fma_f32 v[104:105], v[238:239], s[16:17], v[104:105] op_sel_hi:[1,0,1]
	global_store_dwordx4 v140, v[102:105], s[58:59] offset:576
	s_waitcnt vmcnt(12)
	v_pk_add_f32 v[240:241], v[240:241], v[150:151] op_sel_hi:[1,0] neg_lo:[0,1] neg_hi:[0,1]
	v_pk_add_f32 v[242:243], v[242:243], v[150:151] op_sel_hi:[1,0] neg_lo:[0,1] neg_hi:[0,1]
	v_pk_mul_f32 v[240:241], v[240:241], v[150:151] op_sel:[0,1] op_sel_hi:[1,1]
	v_pk_mul_f32 v[242:243], v[242:243], v[150:151] op_sel:[0,1] op_sel_hi:[1,1]
	v_pk_fma_f32 v[240:241], v[240:241], v[176:177], v[186:187]
	v_pk_fma_f32 v[242:243], v[242:243], v[178:179], v[188:189]
	v_pk_fma_f32 v[86:87], v[240:241], s[16:17], v[86:87] op_sel_hi:[1,0,1]
	v_pk_fma_f32 v[88:89], v[242:243], s[16:17], v[88:89] op_sel_hi:[1,0,1]
	global_store_dwordx4 v140, v[86:89], s[60:61] offset:576
	s_waitcnt vmcnt(13)
	v_pk_add_f32 v[244:245], v[244:245], v[154:155] op_sel_hi:[1,0] neg_lo:[0,1] neg_hi:[0,1]
	v_pk_add_f32 v[246:247], v[246:247], v[154:155] op_sel_hi:[1,0] neg_lo:[0,1] neg_hi:[0,1]
	v_pk_mul_f32 v[244:245], v[244:245], v[154:155] op_sel:[0,1] op_sel_hi:[1,1]
	v_pk_mul_f32 v[246:247], v[246:247], v[154:155] op_sel:[0,1] op_sel_hi:[1,1]
	v_pk_fma_f32 v[244:245], v[244:245], v[176:177], v[186:187]
	v_pk_fma_f32 v[246:247], v[246:247], v[178:179], v[188:189]
	v_pk_fma_f32 v[70:71], v[244:245], s[16:17], v[70:71] op_sel_hi:[1,0,1]
	v_pk_fma_f32 v[72:73], v[246:247], s[16:17], v[72:73] op_sel_hi:[1,0,1]
	global_store_dwordx4 v140, v[70:73], s[62:63] offset:576
	s_waitcnt vmcnt(14)
	v_pk_add_f32 v[190:191], v[190:191], v[156:157] op_sel_hi:[1,0] neg_lo:[0,1] neg_hi:[0,1]
	v_pk_add_f32 v[192:193], v[192:193], v[156:157] op_sel_hi:[1,0] neg_lo:[0,1] neg_hi:[0,1]
	v_pk_mul_f32 v[190:191], v[190:191], v[156:157] op_sel:[0,1] op_sel_hi:[1,1]
	v_pk_mul_f32 v[192:193], v[192:193], v[156:157] op_sel:[0,1] op_sel_hi:[1,1]
	v_pk_fma_f32 v[190:191], v[190:191], v[176:177], v[186:187]
	v_pk_fma_f32 v[192:193], v[192:193], v[178:179], v[188:189]
	v_pk_fma_f32 v[54:55], v[190:191], s[16:17], v[54:55] op_sel_hi:[1,0,1]
	v_pk_fma_f32 v[56:57], v[192:193], s[16:17], v[56:57] op_sel_hi:[1,0,1]
	global_store_dwordx4 v140, v[54:57], s[64:65] offset:576
	s_waitcnt vmcnt(15)
	v_pk_add_f32 v[194:195], v[194:195], v[162:163] op_sel_hi:[1,0] neg_lo:[0,1] neg_hi:[0,1]
	v_pk_add_f32 v[196:197], v[196:197], v[162:163] op_sel_hi:[1,0] neg_lo:[0,1] neg_hi:[0,1]
	v_pk_mul_f32 v[194:195], v[194:195], v[162:163] op_sel:[0,1] op_sel_hi:[1,1]
	v_pk_mul_f32 v[196:197], v[196:197], v[162:163] op_sel:[0,1] op_sel_hi:[1,1]
	v_pk_fma_f32 v[194:195], v[194:195], v[176:177], v[186:187]
	v_pk_fma_f32 v[196:197], v[196:197], v[178:179], v[188:189]
	v_pk_fma_f32 v[38:39], v[194:195], s[16:17], v[38:39] op_sel_hi:[1,0,1]
	v_pk_fma_f32 v[40:41], v[196:197], s[16:17], v[40:41] op_sel_hi:[1,0,1]
	global_store_dwordx4 v140, v[38:41], s[66:67] offset:576
	s_waitcnt vmcnt(14)
	v_pk_add_f32 v[198:199], v[198:199], v[164:165] op_sel_hi:[1,0] neg_lo:[0,1] neg_hi:[0,1]
	v_pk_add_f32 v[200:201], v[200:201], v[164:165] op_sel_hi:[1,0] neg_lo:[0,1] neg_hi:[0,1]
	v_pk_mul_f32 v[198:199], v[198:199], v[164:165] op_sel:[0,1] op_sel_hi:[1,1]
	v_pk_mul_f32 v[200:201], v[200:201], v[164:165] op_sel:[0,1] op_sel_hi:[1,1]
	v_pk_fma_f32 v[198:199], v[198:199], v[176:177], v[186:187]
	v_pk_fma_f32 v[200:201], v[200:201], v[178:179], v[188:189]
	v_pk_fma_f32 v[22:23], v[198:199], s[16:17], v[22:23] op_sel_hi:[1,0,1]
	v_pk_fma_f32 v[24:25], v[200:201], s[16:17], v[24:25] op_sel_hi:[1,0,1]
	global_store_dwordx4 v140, v[22:25], s[68:69] offset:576
	s_waitcnt vmcnt(13)
	v_pk_add_f32 v[204:205], v[204:205], v[166:167] op_sel_hi:[1,0] neg_lo:[0,1] neg_hi:[0,1]
	v_pk_add_f32 v[206:207], v[206:207], v[166:167] op_sel_hi:[1,0] neg_lo:[0,1] neg_hi:[0,1]
	v_pk_mul_f32 v[204:205], v[204:205], v[166:167] op_sel:[0,1] op_sel_hi:[1,1]
	v_pk_mul_f32 v[206:207], v[206:207], v[166:167] op_sel:[0,1] op_sel_hi:[1,1]
	v_pk_fma_f32 v[204:205], v[204:205], v[176:177], v[186:187]
	v_pk_fma_f32 v[206:207], v[206:207], v[178:179], v[188:189]
	v_pk_fma_f32 v[0:1], v[204:205], s[16:17], v[0:1] op_sel_hi:[1,0,1]
	v_pk_fma_f32 v[2:3], v[206:207], s[16:17], v[2:3] op_sel_hi:[1,0,1]
	global_store_dwordx4 v140, v[0:3], s[70:71] offset:576
	s_branch .Llz_join
; DI bf16x4 pack4(float a, float b, float c, float d) { u32x2v u; u.x = pk2(a, b); u.y = pk2(c, d); return __builtin_bit_cast(bf16x4, u); }
;   DI void operator()(const f32x4 (&acc)[2][2][4][2], const pg8::Unit& u, int wr, int wc, int fr, int fq) const {
;     bf16_t* MERGED = (reinterpret_cast<bf16_t*>(p.ws + OFF_GA));
; #pragma unroll
;     for (int ai = 0; ai < 2; ++ai)
; #pragma unroll
;       for (int m = 0; m < 4; ++m) {
;         const int row = u.pm * 256 + 128 * ai + 64 * wr + 16 * m + fr;
; #pragma unroll
;         for (int bj = 0; bj < 2; ++bj)
; #pragma unroll
;           for (int n = 0; n < 2; ++n) {
;             const size_t idx = (size_t)row * 1024 + u.pn * 256 + 128 * bj + 32 * wc + 16 * n + 4 * fq;
;             const f32x4 a = acc[ai][bj][m][n];
;             if (MODE == 0) {
;               const unsigned g = *reinterpret_cast<const unsigned*>(reinterpret_cast<const unsigned char*>(p.ws + OFF_RB) + idx);
;               const float k = 1.f / 255.f;
;               st4(MERGED + idx, pack4((float)(g & 255u) * k * a[0], (float)((g >> 8) & 255u) * k * a[1], (float)((g >> 16) & 255u) * k * a[2], (float)(g >> 24) * k * a[3]));
;             } else {
;               f32x4 x = *reinterpret_cast<const f32x4*>(p.out + idx);
;               x = x * ALPHA + a;
;               *reinterpret_cast<f32x4*>(p.out + idx) = x;
;             }
;           }
;       }
.Llz_plain:
	v_lshl_add_u32 v140, s10, 8, v21
	s_lshl_b32 s10, s11, 8
	v_ashrrev_i32_e32 v141, 31, v140
	s_ashr_i32 s11, s10, 31
	v_lshlrev_b64 v[144:145], 12, v[140:141]
	v_readlane_b32 s14, v249, 4
	v_readlane_b32 s15, v249, 5
	s_lshl_b64 s[10:11], s[10:11], 2
	v_readlane_b32 s12, v251, 6
	v_readlane_b32 s13, v251, 7
	s_mov_b32 s16, 0x3fd744fd
	s_nop 1
	v_lshl_add_u64 v[144:145], s[14:15], 0, v[144:145]
	v_lshl_add_u64 v[144:145], v[144:145], 0, s[10:11]
	v_lshl_add_u64 v[144:145], v[144:145], 0, s[12:13]
	v_lshl_add_u64 v[148:149], v[144:145], 0, v[16:17]
	s_mov_b64 s[12:13], 0x10000
	v_lshl_add_u64 v[150:151], v[148:149], 0, s[12:13]
	s_mov_b64 s[14:15], 0x20000
	v_lshl_add_u64 v[154:155], v[148:149], 0, s[14:15]
	s_mov_b64 s[12:13], 0x30000
	v_lshl_add_u64 v[156:157], v[148:149], 0, s[12:13]
	s_mov_b64 s[14:15], 0x80000
	v_lshl_add_u64 v[162:163], v[148:149], 0, s[14:15]
	s_mov_b64 s[12:13], 0x90000
	v_lshl_add_u64 v[164:165], v[148:149], 0, s[12:13]
	s_mov_b64 s[14:15], 0xa0000
	v_lshl_add_u64 v[166:167], v[148:149], 0, s[14:15]
	s_mov_b64 s[12:13], 0xb0000
	v_lshl_add_u64 v[168:169], v[148:149], 0, s[12:13]
	global_load_dwordx4 v[170:173], v[148:149], off
	global_load_dwordx4 v[174:177], v[148:149], off offset:64
	global_load_dwordx4 v[178:181], v[148:149], off offset:512
	global_load_dwordx4 v[186:189], v[148:149], off offset:576
	global_load_dwordx4 v[190:193], v[150:151], off
	global_load_dwordx4 v[194:197], v[150:151], off offset:64
	global_load_dwordx4 v[198:201], v[150:151], off offset:512
	global_load_dwordx4 v[204:207], v[150:151], off offset:576
	global_load_dwordx4 v[208:211], v[154:155], off
	global_load_dwordx4 v[212:215], v[154:155], off offset:64
	global_load_dwordx4 v[216:219], v[154:155], off offset:512
	global_load_dwordx4 v[220:223], v[154:155], off offset:576
	global_load_dwordx4 v[224:227], v[156:157], off
	global_load_dwordx4 v[228:231], v[156:157], off offset:64
	global_load_dwordx4 v[232:235], v[156:157], off offset:512
	global_load_dwordx4 v[236:239], v[156:157], off offset:576
	s_waitcnt vmcnt(15)
	v_pk_fma_f32 v[132:133], v[172:173], s[16:17], v[132:133] op_sel_hi:[1,0,1]
	v_pk_fma_f32 v[130:131], v[170:171], s[16:17], v[130:131] op_sel_hi:[1,0,1]
	global_store_dwordx4 v[148:149], v[130:133], off
	global_load_dwordx4 v[170:173], v[162:163], off
	s_waitcnt vmcnt(16)
	v_pk_fma_f32 v[128:129], v[176:177], s[16:17], v[128:129] op_sel_hi:[1,0,1]
	v_pk_fma_f32 v[126:127], v[174:175], s[16:17], v[126:127] op_sel_hi:[1,0,1]
	global_store_dwordx4 v[148:149], v[126:129], off offset:64
	global_load_dwordx4 v[174:177], v[162:163], off offset:64
	s_waitcnt vmcnt(17)
	v_pk_fma_f32 v[124:125], v[180:181], s[16:17], v[124:125] op_sel_hi:[1,0,1]
	v_pk_fma_f32 v[122:123], v[178:179], s[16:17], v[122:123] op_sel_hi:[1,0,1]
	global_store_dwordx4 v[148:149], v[122:125], off offset:512
	global_load_dwordx4 v[178:181], v[162:163], off offset:512
	s_waitcnt vmcnt(18)
	v_pk_fma_f32 v[120:121], v[188:189], s[16:17], v[120:121] op_sel_hi:[1,0,1]
	v_pk_fma_f32 v[118:119], v[186:187], s[16:17], v[118:119] op_sel_hi:[1,0,1]
	global_store_dwordx4 v[148:149], v[118:121], off offset:576
	global_load_dwordx4 v[186:189], v[162:163], off offset:576
	s_waitcnt vmcnt(19)
	v_pk_fma_f32 v[116:117], v[192:193], s[16:17], v[116:117] op_sel_hi:[1,0,1]
	v_pk_fma_f32 v[114:115], v[190:191], s[16:17], v[114:115] op_sel_hi:[1,0,1]
	global_store_dwordx4 v[150:151], v[114:117], off
	global_load_dwordx4 v[190:193], v[164:165], off
	s_waitcnt vmcnt(20)
	v_pk_fma_f32 v[112:113], v[196:197], s[16:17], v[112:113] op_sel_hi:[1,0,1]
	v_pk_fma_f32 v[110:111], v[194:195], s[16:17], v[110:111] op_sel_hi:[1,0,1]
	global_store_dwordx4 v[150:151], v[110:113], off offset:64
	global_load_dwordx4 v[194:197], v[164:165], off offset:64
	s_waitcnt vmcnt(21)
	v_pk_fma_f32 v[108:109], v[200:201], s[16:17], v[108:109] op_sel_hi:[1,0,1]
	v_pk_fma_f32 v[106:107], v[198:199], s[16:17], v[106:107] op_sel_hi:[1,0,1]
	global_store_dwordx4 v[150:151], v[106:109], off offset:512
	global_load_dwordx4 v[198:201], v[164:165], off offset:512
	s_waitcnt vmcnt(22)
	v_pk_fma_f32 v[104:105], v[206:207], s[16:17], v[104:105] op_sel_hi:[1,0,1]
	v_pk_fma_f32 v[102:103], v[204:205], s[16:17], v[102:103] op_sel_hi:[1,0,1]
	global_store_dwordx4 v[150:151], v[102:105], off offset:576
	global_load_dwordx4 v[204:207], v[164:165], off offset:576
	s_waitcnt vmcnt(23)
	v_pk_fma_f32 v[100:101], v[210:211], s[16:17], v[100:101] op_sel_hi:[1,0,1]
	v_pk_fma_f32 v[98:99], v[208:209], s[16:17], v[98:99] op_sel_hi:[1,0,1]
	global_store_dwordx4 v[154:155], v[98:101], off
	global_load_dwordx4 v[208:211], v[166:167], off
	s_waitcnt vmcnt(24)
	v_pk_fma_f32 v[96:97], v[214:215], s[16:17], v[96:97] op_sel_hi:[1,0,1]
	v_pk_fma_f32 v[94:95], v[212:213], s[16:17], v[94:95] op_sel_hi:[1,0,1]
	global_store_dwordx4 v[154:155], v[94:97], off offset:64
	global_load_dwordx4 v[212:215], v[166:167], off offset:64
	s_waitcnt vmcnt(25)
	v_pk_fma_f32 v[92:93], v[218:219], s[16:17], v[92:93] op_sel_hi:[1,0,1]
	v_pk_fma_f32 v[90:91], v[216:217], s[16:17], v[90:91] op_sel_hi:[1,0,1]
	global_store_dwordx4 v[154:155], v[90:93], off offset:512
	global_load_dwordx4 v[216:219], v[166:167], off offset:512
	s_waitcnt vmcnt(26)
; #define PG8_WAIT_V(n) asm volatile("s_waitcnt vmcnt(" #n ")" ::: "memory")
; #define PG8_BAR __builtin_amdgcn_s_barrier()
; template <class Epi, class Sched>
; __device__ __forceinline__ void gemm_phase(PG8_LAS unsigned char* lds, const Gemm g, const Sched& S, const Epi& E) {
;     ...
;         if constexpr (!Epi::AFTER_DRAIN) { E(acc, cur, wr, wc, fr, fq); S.done(cur); }
;         if (!has_next) break;
; #pragma unroll
;         for (int a = 0; a < 2; ++a)
; #pragma unroll
;             for (int b = 0; b < 2; ++b)
; #pragma unroll
;                 for (int m = 0; m < 4; ++m)
; #pragma unroll
;                     for (int n = 0; n < 2; ++n) acc[a][b][m][n] = (f32x4){0.f, 0.f, 0.f, 0.f};
;         cur = nxt; cA = nA; cB = nB; ++ui;
;     }
;     PG8_WAIT_V(0);
;     if (wr == 0) PG8_BAR;
;     PG8_BAR;
;   DI void operator()(const f32x4 (&acc)[2][2][4][2], const pg8::Unit& u, int wr, int wc, int fr, int fq) const {
;     ...
;               f32x4 x = *reinterpret_cast<const f32x4*>(p.out + idx);
;               x = x * ALPHA + a;
;               *reinterpret_cast<f32x4*>(p.out + idx) = x;
	v_pk_fma_f32 v[88:89], v[222:223], s[16:17], v[88:89] op_sel_hi:[1,0,1]
	v_pk_fma_f32 v[86:87], v[220:221], s[16:17], v[86:87] op_sel_hi:[1,0,1]
	global_store_dwordx4 v[154:155], v[86:89], off offset:576
	global_load_dwordx4 v[220:223], v[166:167], off offset:576
	s_waitcnt vmcnt(27)
	v_pk_fma_f32 v[84:85], v[226:227], s[16:17], v[84:85] op_sel_hi:[1,0,1]
	v_pk_fma_f32 v[82:83], v[224:225], s[16:17], v[82:83] op_sel_hi:[1,0,1]
	global_store_dwordx4 v[156:157], v[82:85], off
	global_load_dwordx4 v[224:227], v[168:169], off
	s_waitcnt vmcnt(28)
	v_pk_fma_f32 v[80:81], v[230:231], s[16:17], v[80:81] op_sel_hi:[1,0,1]
	v_pk_fma_f32 v[78:79], v[228:229], s[16:17], v[78:79] op_sel_hi:[1,0,1]
	global_store_dwordx4 v[156:157], v[78:81], off offset:64
	global_load_dwordx4 v[228:231], v[168:169], off offset:64
	s_waitcnt vmcnt(29)
	v_pk_fma_f32 v[76:77], v[234:235], s[16:17], v[76:77] op_sel_hi:[1,0,1]
	v_pk_fma_f32 v[74:75], v[232:233], s[16:17], v[74:75] op_sel_hi:[1,0,1]
	global_store_dwordx4 v[156:157], v[74:77], off offset:512
	global_load_dwordx4 v[232:235], v[168:169], off offset:512
	s_waitcnt vmcnt(30)
	v_pk_fma_f32 v[72:73], v[238:239], s[16:17], v[72:73] op_sel_hi:[1,0,1]
	v_pk_fma_f32 v[70:71], v[236:237], s[16:17], v[70:71] op_sel_hi:[1,0,1]
	global_store_dwordx4 v[156:157], v[70:73], off offset:576
	global_load_dwordx4 v[236:239], v[168:169], off offset:576
	s_waitcnt vmcnt(30)
	v_pk_fma_f32 v[68:69], v[172:173], s[16:17], v[68:69] op_sel_hi:[1,0,1]
	v_pk_fma_f32 v[66:67], v[170:171], s[16:17], v[66:67] op_sel_hi:[1,0,1]
	global_store_dwordx4 v[162:163], v[66:69], off
	s_waitcnt vmcnt(29)
	v_pk_fma_f32 v[64:65], v[176:177], s[16:17], v[64:65] op_sel_hi:[1,0,1]
	v_pk_fma_f32 v[62:63], v[174:175], s[16:17], v[62:63] op_sel_hi:[1,0,1]
	global_store_dwordx4 v[162:163], v[62:65], off offset:64
	s_waitcnt vmcnt(28)
	v_pk_fma_f32 v[60:61], v[180:181], s[16:17], v[60:61] op_sel_hi:[1,0,1]
	v_pk_fma_f32 v[58:59], v[178:179], s[16:17], v[58:59] op_sel_hi:[1,0,1]
	global_store_dwordx4 v[162:163], v[58:61], off offset:512
	s_waitcnt vmcnt(27)
	v_pk_fma_f32 v[56:57], v[188:189], s[16:17], v[56:57] op_sel_hi:[1,0,1]
	v_pk_fma_f32 v[54:55], v[186:187], s[16:17], v[54:55] op_sel_hi:[1,0,1]
	global_store_dwordx4 v[162:163], v[54:57], off offset:576
	s_waitcnt vmcnt(26)
	v_pk_fma_f32 v[52:53], v[192:193], s[16:17], v[52:53] op_sel_hi:[1,0,1]
	v_pk_fma_f32 v[50:51], v[190:191], s[16:17], v[50:51] op_sel_hi:[1,0,1]
	global_store_dwordx4 v[164:165], v[50:53], off
	s_waitcnt vmcnt(25)
	v_pk_fma_f32 v[48:49], v[196:197], s[16:17], v[48:49] op_sel_hi:[1,0,1]
	v_pk_fma_f32 v[46:47], v[194:195], s[16:17], v[46:47] op_sel_hi:[1,0,1]
	global_store_dwordx4 v[164:165], v[46:49], off offset:64
	s_waitcnt vmcnt(24)
	v_pk_fma_f32 v[44:45], v[200:201], s[16:17], v[44:45] op_sel_hi:[1,0,1]
	v_pk_fma_f32 v[42:43], v[198:199], s[16:17], v[42:43] op_sel_hi:[1,0,1]
	global_store_dwordx4 v[164:165], v[42:45], off offset:512
	s_waitcnt vmcnt(23)
	v_pk_fma_f32 v[40:41], v[206:207], s[16:17], v[40:41] op_sel_hi:[1,0,1]
	v_pk_fma_f32 v[38:39], v[204:205], s[16:17], v[38:39] op_sel_hi:[1,0,1]
	global_store_dwordx4 v[164:165], v[38:41], off offset:576
	s_waitcnt vmcnt(22)
	v_pk_fma_f32 v[36:37], v[210:211], s[16:17], v[36:37] op_sel_hi:[1,0,1]
	v_pk_fma_f32 v[34:35], v[208:209], s[16:17], v[34:35] op_sel_hi:[1,0,1]
	global_store_dwordx4 v[166:167], v[34:37], off
	s_waitcnt vmcnt(21)
	v_pk_fma_f32 v[32:33], v[214:215], s[16:17], v[32:33] op_sel_hi:[1,0,1]
	v_pk_fma_f32 v[30:31], v[212:213], s[16:17], v[30:31] op_sel_hi:[1,0,1]
	global_store_dwordx4 v[166:167], v[30:33], off offset:64
	s_waitcnt vmcnt(20)
	v_pk_fma_f32 v[28:29], v[218:219], s[16:17], v[28:29] op_sel_hi:[1,0,1]
	v_pk_fma_f32 v[26:27], v[216:217], s[16:17], v[26:27] op_sel_hi:[1,0,1]
	global_store_dwordx4 v[166:167], v[26:29], off offset:512
	s_waitcnt vmcnt(19)
	v_pk_fma_f32 v[24:25], v[222:223], s[16:17], v[24:25] op_sel_hi:[1,0,1]
	v_pk_fma_f32 v[22:23], v[220:221], s[16:17], v[22:23] op_sel_hi:[1,0,1]
	global_store_dwordx4 v[166:167], v[22:25], off offset:576
	s_waitcnt vmcnt(18)
	v_pk_fma_f32 v[14:15], v[226:227], s[16:17], v[14:15] op_sel_hi:[1,0,1]
	v_pk_fma_f32 v[12:13], v[224:225], s[16:17], v[12:13] op_sel_hi:[1,0,1]
	global_store_dwordx4 v[168:169], v[12:15], off
	s_waitcnt vmcnt(17)
	v_pk_fma_f32 v[10:11], v[230:231], s[16:17], v[10:11] op_sel_hi:[1,0,1]
	v_pk_fma_f32 v[8:9], v[228:229], s[16:17], v[8:9] op_sel_hi:[1,0,1]
	global_store_dwordx4 v[168:169], v[8:11], off offset:64
	s_waitcnt vmcnt(16)
	v_pk_fma_f32 v[6:7], v[234:235], s[16:17], v[6:7] op_sel_hi:[1,0,1]
	v_pk_fma_f32 v[4:5], v[232:233], s[16:17], v[4:5] op_sel_hi:[1,0,1]
	global_store_dwordx4 v[168:169], v[4:7], off offset:512
	s_waitcnt vmcnt(15)
	v_pk_fma_f32 v[2:3], v[238:239], s[16:17], v[2:3] op_sel_hi:[1,0,1]
	v_pk_fma_f32 v[0:1], v[236:237], s[16:17], v[0:1] op_sel_hi:[1,0,1]
	global_store_dwordx4 v[168:169], v[0:3], off offset:576
.Llz_join:
	s_mov_b32 s11, s2
	s_mov_b32 s10, s4
	s_mov_b64 s[14:15], s[8:9]
	s_mov_b64 s[12:13], s[6:7]
	s_and_b64 vcc, exec, s[0:1]
	s_cbranch_vccz .LBB0_2751
	s_waitcnt vmcnt(0)
	s_cmpk_gt_u32 s20, 0xff
	s_cbranch_scc1 .LBB0_2758
	s_barrier

; DI int otid() { int t = threadIdx.x; asm volatile("" : "+v"(t)); return t; }
; DI void phase_ln(const Params& p, int layer, char* smem) {
;   const int tid = otid(), lane = tid & 63;
;   {
;     const int stride = gridDim.x * NWAVES;
;     const float* g = p.ln_g + layer * 1024; const float* b = p.ln_b + layer * 1024;
;     for (int row = blockIdx.x * NWAVES + (tid >> 6); row < MT; row += 2 * stride) {
;       const int row2 = row + stride;
;       if (row2 < MT) ln_rows2(p.out + (size_t)row * 1024, p.out + (size_t)row2 * 1024, g, b, p.out + (size_t)row * 1024, (reinterpret_cast<bf16_t*>(p.ws + OFF_XB)) + (size_t)row * 1024, p.out + (size_t)row2 * 1024, (reinterpret_cast<bf16_t*>(p.ws + OFF_XB)) + (size_t)row2 * 1024, lane);
;       else ln_row_wave(p.out + (size_t)row * 1024, g, b, p.out + (size_t)row * 1024, (reinterpret_cast<bf16_t*>(p.ws + OFF_XB)) + (size_t)row * 1024, lane);
;     }
;   }
;   if (layer + 1 < DEPTH) convert_layer(p, layer + 1, smem);
.LBB0_2765:
	s_or_b64 exec, exec, s[0:1]
	v_mov_b32_e32 v1, v153
	s_barrier
	v_readlane_b32 s0, v249, 9
	v_ashrrev_i32_e32 v0, 6, v1
	s_nop 0
	v_add_u32_e32 v0, s0, v0
	s_mov_b32 s0, 0x10200
	v_cmp_gt_i32_e32 vcc, s0, v0
	s_and_saveexec_b64 s[0:1], vcc
	v_readlane_b32 s8, v251, 5
	s_mov_b32 s9, 0x101ff
	s_cbranch_execz .LBB0_2772
	v_readlane_b32 s2, v251, 6
	v_readlane_b32 s3, v251, 7
	s_mov_b32 s5, s3
	v_readlane_b32 s2, v251, 8
	v_readlane_b32 s3, v251, 9
	s_mov_b32 s3, s5
	s_lshl_b32 s4, s2, 10
	v_writelane_b32 v251, s2, 6
	v_readlane_b32 s36, v249, 26
	v_readlane_b32 s50, v249, 40
	v_writelane_b32 v251, s3, 7
	s_lshl_b64 s[2:3], s[4:5], 2
	v_readlane_b32 s51, v249, 41
	s_add_u32 s4, s50, s2
	v_readlane_b32 s48, v249, 38
	s_addc_u32 s5, s51, s3
	v_readlane_b32 s49, v249, 39
	s_add_u32 s2, s48, s2
	v_and_b32_e32 v4, 63, v1
	s_addc_u32 s3, s49, s3
	v_lshlrev_b32_e32 v16, 4, v4
	v_or_b32_e32 v1, 0xc0, v4
	v_lshl_add_u64 v[6:7], s[2:3], 0, v[16:17]
	v_lshl_add_u64 v[8:9], s[4:5], 0, v[16:17]
	v_readlane_b32 s2, v249, 0
	v_readlane_b32 s4, v249, 2
	v_lshlrev_b32_e32 v10, 2, v4
	v_lshlrev_b32_e32 v2, 2, v1
	v_lshlrev_b32_e32 v18, 3, v1
	v_mov_b32_e32 v19, v17
	v_readlane_b32 s3, v249, 1
	v_readlane_b32 s6, v249, 4
	v_readlane_b32 s7, v249, 5
	v_or_b32_e32 v12, 0x100, v10
	v_or_b32_e32 v14, 0x200, v10
	v_lshl_add_u64 v[18:19], s[2:3], 0, v[18:19]
	v_lshl_add_u64 v[22:23], s[6:7], 0, v[16:17]
	s_mov_b64 s[2:3], 0
	v_lshlrev_b32_e32 v24, 1, v2
	v_readlane_b32 s37, v249, 27
	v_readlane_b32 s38, v249, 28
	v_readlane_b32 s39, v249, 29
	v_readlane_b32 s40, v249, 30
	v_readlane_b32 s41, v249, 31
	v_readlane_b32 s42, v249, 32
	v_readlane_b32 s43, v249, 33
	v_readlane_b32 s44, v249, 34
	v_readlane_b32 s45, v249, 35
	v_readlane_b32 s46, v249, 36
	v_readlane_b32 s47, v249, 37
	v_readlane_b32 s5, v249, 3
	v_readlane_b32 s56, v249, 0
	v_readlane_b32 s57, v249, 1
	s_add_u32 s56, s56, 0x2b234000
	s_addc_u32 s57, s57, 0
	v_readlane_b32 s58, v251, 5
	s_lshl_b32 s58, s58, 3
	s_sub_u32 s58, s56, s58
	s_subb_u32 s59, s57, 0
	v_readlane_b32 s60, v251, 8
	s_cmp_eq_u32 s60, 3
	s_cselect_b64 s[60:61], -1, 0
	s_branch .LBB0_2768

; DI bf16x4 pack4(float a, float b, float c, float d) { u32x2v u; u.x = pk2(a, b); u.y = pk2(c, d); return __builtin_bit_cast(bf16x4, u); }
; DI float wave_sum(float x) { x = row_sum16(x); F2 a = swap16(x); x = a.lo + a.hi; F2 b = swap32(x); return b.lo + b.hi; }
; DI void ln_row_wave(const float* src, const float* g, const float* b, float* d32, bf16_t* db, int lane) {
;   float4 v[4]; float s = 0.f;
; #pragma unroll
;   for (int i = 0; i < 4; ++i) { v[i] = reinterpret_cast<const float4*>(src)[lane + 64 * i]; s += v[i].x + v[i].y + v[i].z + v[i].w; }
;   s = wave_sum(s);
;   const float mu = s * (1.f / 1024.f);
;   float q = 0.f;
; #pragma unroll
;   for (int i = 0; i < 4; ++i) { float a = v[i].x - mu, bb = v[i].y - mu, c = v[i].z - mu, d = v[i].w - mu; q += a * a + bb * bb + c * c + d * d; }
;   q = wave_sum(q);
;   const float rstd = rsqrtf(q * (1.f / 1024.f) + LN_EPS);
; #pragma unroll
;   for (int i = 0; i < 4; ++i) {
;     float4 gg = reinterpret_cast<const float4*>(g)[lane + 64 * i], bb = reinterpret_cast<const float4*>(b)[lane + 64 * i];
;     float4 o;
;     o.x = (v[i].x - mu) * rstd * gg.x + bb.x; o.y = (v[i].y - mu) * rstd * gg.y + bb.y;
;     o.z = (v[i].z - mu) * rstd * gg.z + bb.z; o.w = (v[i].w - mu) * rstd * gg.w + bb.w;
;     reinterpret_cast<float4*>(d32)[lane + 64 * i] = o;
;     st4(db + 4 * (lane + 64 * i), pack4(o.x, o.y, o.z, o.w));
;   }
; }
.LBB0_2768:
	v_readlane_b32 s4, v249, 2
	v_readlane_b32 s5, v249, 3
	v_ashrrev_i32_e32 v1, 31, v0
	v_readlane_b32 s4, v249, 0
	v_add_u32_e32 v26, s8, v0
	v_lshlrev_b64 v[40:41], 10, v[0:1]
	v_lshlrev_b64 v[0:1], 12, v[0:1]
	v_readlane_b32 s6, v249, 4
	v_readlane_b32 s7, v249, 5
	v_readlane_b32 s5, v249, 1
	v_cmp_lt_i32_e32 vcc, s9, v26
	v_lshl_add_u64 v[36:37], s[6:7], 0, v[0:1]
	v_lshl_add_u64 v[28:29], v[40:41], 1, s[4:5]
	v_lshlrev_b32_e32 v16, 4, v4
	v_lshlrev_b32_e32 v34, 1, v10
	v_lshlrev_b32_e32 v32, 1, v12
	v_lshlrev_b32_e32 v30, 1, v14
	s_and_saveexec_b64 s[4:5], vcc
	s_xor_b64 s[4:5], exec, s[4:5]
	s_cbranch_execz .LBB0_2770
	v_lshl_add_u64 v[58:59], v[36:37], 0, v[16:17]
	global_load_dwordx4 v[0:3], v[58:59], off offset:3072
	global_load_dwordx4 v[36:39], v[58:59], off
	global_load_dwordx4 v[42:45], v[58:59], off offset:1024
	global_load_dwordx4 v[46:49], v[58:59], off offset:2048
	global_load_dwordx4 v[50:53], v[6:7], off
	global_load_dwordx4 v[54:57], v[8:9], off
	s_mov_b32 s6, 0x800000
	v_mov_b32_e32 v35, v17
	v_lshl_add_u64 v[34:35], v[28:29], 0, v[34:35]
	v_mov_b32_e32 v33, v17
	v_lshl_add_u64 v[32:33], v[28:29], 0, v[32:33]
	v_mov_b32_e32 v31, v17
	v_lshl_add_u64 v[28:29], v[28:29], 0, v[30:31]
	s_waitcnt vmcnt(5)
	v_add_f32_e32 v5, v0, v1
	s_waitcnt vmcnt(4)
	v_add_f32_e32 v11, v36, v37
	s_waitcnt vmcnt(3)
	v_add_f32_e32 v13, v42, v43
	v_add_f32_e32 v11, v11, v38
	s_waitcnt vmcnt(2)
	v_add_f32_e32 v15, v46, v47
	v_add_f32_e32 v13, v13, v44
	v_add_f32_e32 v11, v11, v39
	v_add_f32_e32 v15, v15, v48
	v_add_f32_e32 v13, v13, v45
	v_add_f32_e32 v11, 0, v11
	v_add_f32_e32 v5, v5, v2
	v_add_f32_e32 v15, v15, v49
	v_add_f32_e32 v11, v11, v13
	v_add_f32_e32 v5, v5, v3
	v_add_f32_e32 v11, v11, v15
	v_add_f32_e32 v5, v11, v5
	s_nop 1
	v_add_f32_dpp v5, v5, v5 quad_perm:[1,0,3,2] row_mask:0xf bank_mask:0xf bound_ctrl:1
	s_nop 1
	v_add_f32_dpp v5, v5, v5 quad_perm:[2,3,0,1] row_mask:0xf bank_mask:0xf bound_ctrl:1
	s_nop 1
	v_add_f32_dpp v5, v5, v5 row_half_mirror row_mask:0xf bank_mask:0xf bound_ctrl:1
	s_nop 1
	v_add_f32_dpp v5, v5, v5 row_mirror row_mask:0xf bank_mask:0xf bound_ctrl:1
	v_mov_b32_e32 v11, v5
	s_nop 1
	v_permlane16_swap_b32_e32 v5, v11
	v_add_f32_e32 v5, v5, v11
	v_mov_b32_e32 v11, v5
	s_nop 1
	v_permlane32_swap_b32_e32 v5, v11
	v_add_f32_e32 v5, v5, v11
	v_mul_f32_e32 v16, 0x3a800000, v5
	v_mov_b32_e32 v100, v16
	v_pk_add_f32 v[36:37], v[36:37], v[16:17] op_sel_hi:[1,0] neg_lo:[0,1] neg_hi:[0,1]
	v_pk_add_f32 v[42:43], v[42:43], v[16:17] op_sel_hi:[1,0] neg_lo:[0,1] neg_hi:[0,1]
	v_pk_add_f32 v[38:39], v[38:39], v[16:17] op_sel_hi:[1,0] neg_lo:[0,1] neg_hi:[0,1]
	v_pk_add_f32 v[44:45], v[44:45], v[16:17] op_sel_hi:[1,0] neg_lo:[0,1] neg_hi:[0,1]
	v_pk_add_f32 v[46:47], v[46:47], v[16:17] op_sel_hi:[1,0] neg_lo:[0,1] neg_hi:[0,1]
	v_pk_add_f32 v[60:61], v[0:1], v[16:17] op_sel_hi:[1,0] neg_lo:[0,1] neg_hi:[0,1]
	v_pk_mul_f32 v[0:1], v[36:37], v[36:37]
	v_pk_mul_f32 v[64:65], v[42:43], v[42:43]
	v_pk_add_f32 v[48:49], v[48:49], v[16:17] op_sel_hi:[1,0] neg_lo:[0,1] neg_hi:[0,1]
	v_pk_add_f32 v[62:63], v[2:3], v[16:17] op_sel_hi:[1,0] neg_lo:[0,1] neg_hi:[0,1]
	v_pk_mul_f32 v[2:3], v[38:39], v[38:39]
	v_pk_mul_f32 v[66:67], v[44:45], v[44:45]
	v_pk_mul_f32 v[68:69], v[46:47], v[46:47]
	v_add_f32_e32 v5, v64, v65
	v_add_f32_e32 v0, v0, v1
	v_pk_mul_f32 v[70:71], v[48:49], v[48:49]
	v_pk_mul_f32 v[72:73], v[60:61], v[60:61]
	v_add_f32_e32 v1, v68, v69
	v_add_f32_e32 v5, v66, v5
	v_add_f32_e32 v0, v2, v0
	v_pk_mul_f32 v[74:75], v[62:63], v[62:63]
	v_add_f32_e32 v11, v72, v73
	v_add_f32_e32 v1, v70, v1
	v_add_f32_e32 v5, v67, v5
	v_add_f32_e32 v0, v3, v0
	v_add_f32_e32 v2, v74, v11
	v_add_f32_e32 v1, v71, v1
	v_add_f32_e32 v0, v0, v5
	v_add_f32_e32 v2, v75, v2
	v_add_f32_e32 v0, v1, v0
	v_add_f32_e32 v0, v2, v0
	s_nop 1
	v_add_f32_dpp v0, v0, v0 quad_perm:[1,0,3,2] row_mask:0xf bank_mask:0xf bound_ctrl:1
	s_nop 1
	v_add_f32_dpp v0, v0, v0 quad_perm:[2,3,0,1] row_mask:0xf bank_mask:0xf bound_ctrl:1
	s_nop 1
	v_add_f32_dpp v0, v0, v0 row_half_mirror row_mask:0xf bank_mask:0xf bound_ctrl:1
	s_nop 1
	v_add_f32_dpp v0, v0, v0 row_mirror row_mask:0xf bank_mask:0xf bound_ctrl:1
	v_mov_b32_e32 v1, v0
	s_nop 1
	v_permlane16_swap_b32_e32 v0, v1
	v_add_f32_e32 v0, v0, v1
	v_mov_b32_e32 v1, v0
	s_nop 1
	v_permlane32_swap_b32_e32 v0, v1
	v_add_f32_e32 v0, v0, v1
	v_fmamk_f32 v0, v0, 0x3a800000, v152
	v_mul_f32_e32 v1, 0x4b800000, v0
	v_cmp_gt_f32_e32 vcc, s6, v0
	s_nop 1
	v_cndmask_b32_e32 v0, v0, v1, vcc
	v_rsq_f32_e32 v0, v0
	s_nop 0
	v_mul_f32_e32 v1, 0x45800000, v0
	v_cndmask_b32_e32 v16, v0, v1, vcc
	v_pk_mul_f32 v[0:1], v[36:37], v[16:17] op_sel_hi:[1,0]
	v_pk_mul_f32 v[2:3], v[38:39], v[16:17] op_sel_hi:[1,0]
	s_waitcnt vmcnt(0)
	v_pk_fma_f32 v[0:1], v[50:51], v[0:1], v[54:55]
	v_pk_fma_f32 v[2:3], v[52:53], v[2:3], v[56:57]
	s_and_saveexec_b64 s[62:63], s[60:61]
	global_store_dwordx4 v[58:59], v[0:3], off
	s_mov_b64 exec, s[62:63]
	v_pk_mul_f32 v[38:39], v[42:43], v[16:17] op_sel_hi:[1,0]
	v_pk_mul_f32 v[42:43], v[44:45], v[16:17] op_sel_hi:[1,0]
	v_cvt_pk_bf16_f32 v0, v0, v1
	v_cvt_pk_bf16_f32 v1, v2, v3
	global_store_dwordx2 v[34:35], v[0:1], off
	global_load_dwordx4 v[0:3], v[6:7], off offset:1024
	s_nop 0
	global_load_dwordx4 v[34:37], v[8:9], off offset:1024
	v_pk_mul_f32 v[30:31], v[46:47], v[16:17] op_sel_hi:[1,0]
	s_waitcnt vmcnt(0)
	v_pk_fma_f32 v[0:1], v[38:39], v[0:1], v[34:35]
	v_pk_fma_f32 v[2:3], v[42:43], v[2:3], v[36:37]
	s_and_saveexec_b64 s[62:63], s[60:61]
	global_store_dwordx4 v[58:59], v[0:3], off offset:1024
	s_mov_b64 exec, s[62:63]
	v_pk_mul_f32 v[36:37], v[48:49], v[16:17] op_sel_hi:[1,0]
	s_nop 0
	v_cvt_pk_bf16_f32 v0, v0, v1
	v_cvt_pk_bf16_f32 v1, v2, v3
	global_store_dwordx2 v[32:33], v[0:1], off
	global_load_dwordx4 v[0:3], v[6:7], off offset:2048
	s_nop 0
	global_load_dwordx4 v[32:35], v[8:9], off offset:2048
	s_waitcnt vmcnt(0)
	v_pk_fma_f32 v[0:1], v[30:31], v[0:1], v[32:33]
	v_pk_fma_f32 v[2:3], v[36:37], v[2:3], v[34:35]
	s_and_saveexec_b64 s[62:63], s[60:61]
	global_store_dwordx4 v[58:59], v[0:3], off offset:2048
	s_mov_b64 exec, s[62:63]
	v_pk_mul_f32 v[32:33], v[60:61], v[16:17] op_sel_hi:[1,0]
	v_pk_mul_f32 v[34:35], v[62:63], v[16:17] op_sel_hi:[1,0]
	v_cvt_pk_bf16_f32 v0, v0, v1
	v_cvt_pk_bf16_f32 v1, v2, v3
	global_store_dwordx2 v[28:29], v[0:1], off
	global_load_dwordx4 v[0:3], v[6:7], off offset:3072
	s_nop 0
	global_load_dwordx4 v[28:31], v[8:9], off offset:3072
	s_waitcnt vmcnt(0)
	v_pk_fma_f32 v[0:1], v[32:33], v[0:1], v[28:29]
	v_pk_fma_f32 v[2:3], v[34:35], v[2:3], v[30:31]
	s_and_saveexec_b64 s[62:63], s[60:61]
	global_store_dwordx4 v[58:59], v[0:3], off offset:3072
	s_mov_b64 exec, s[62:63]
	v_mov_b32_e32 v101, v16
	v_lshlrev_b32_e32 v104, 3, v26
	global_store_dwordx2 v104, v[100:101], s[58:59]
; DI float wave_sum(float x) { x = row_sum16(x); F2 a = swap16(x); x = a.lo + a.hi; F2 b = swap32(x); return b.lo + b.hi; }
; DI void ln_rows2(const float* s0, const float* s1, const float* g, const float* b, float* d0, bf16_t* db0, float* d1, bf16_t* db1, int lane) {
;   float4 v0[4], v1[4]; float a0 = 0.f, a1 = 0.f;
; #pragma unroll
;   for (int i = 0; i < 4; ++i) { v0[i] = reinterpret_cast<const float4*>(s0)[lane + 64 * i]; v1[i] = reinterpret_cast<const float4*>(s1)[lane + 64 * i]; }
; #pragma unroll
;   for (int i = 0; i < 4; ++i) { a0 += v0[i].x + v0[i].y + v0[i].z + v0[i].w; a1 += v1[i].x + v1[i].y + v1[i].z + v1[i].w; }
;   a0 = wave_sum(a0); a1 = wave_sum(a1);
;   const float mu0 = a0 * (1.f / 1024.f), mu1 = a1 * (1.f / 1024.f);
;   float q0 = 0.f, q1 = 0.f;
; #pragma unroll
;   for (int i = 0; i < 4; ++i) {
;     { float a = v0[i].x - mu0, bb = v0[i].y - mu0, c = v0[i].z - mu0, d = v0[i].w - mu0; q0 += a * a + bb * bb + c * c + d * d; }
;     { float a = v1[i].x - mu1, bb = v1[i].y - mu1, c = v1[i].z - mu1, d = v1[i].w - mu1; q1 += a * a + bb * bb + c * c + d * d; }
;   }
;   q0 = wave_sum(q0); q1 = wave_sum(q1);
;   const float r0 = rsqrtf(q0 * (1.f / 1024.f) + LN_EPS), r1 = rsqrtf(q1 * (1.f / 1024.f) + LN_EPS);
.LBB0_2770:
	s_andn2_saveexec_b64 s[4:5], s[4:5]
	s_cbranch_execz .LBB0_2767
	v_lshl_add_u64 v[36:37], v[36:37], 0, v[16:17]
	global_load_dwordx4 v[40:43], v[36:37], off
	global_load_dwordx4 v[44:47], v[36:37], off offset:1024
	global_load_dwordx4 v[48:51], v[36:37], off offset:2048
	global_load_dwordx4 v[52:55], v[36:37], off offset:3072
	v_ashrrev_i32_e32 v27, 31, v26
	v_lshlrev_b64 v[0:1], 12, v[26:27]
	v_lshl_add_u64 v[38:39], v[22:23], 0, v[0:1]
	global_load_dwordx4 v[56:59], v[38:39], off offset:3072
	global_load_dwordx4 v[60:63], v[38:39], off
	global_load_dwordx4 v[64:67], v[38:39], off offset:1024
	global_load_dwordx4 v[68:71], v[38:39], off offset:2048
	global_load_dwordx4 v[72:75], v[6:7], off
	global_load_dwordx4 v[76:79], v[8:9], off
	v_readlane_b32 s6, v249, 0
	v_lshlrev_b64 v[0:1], 11, v[26:27]
	v_readlane_b32 s7, v249, 1
	v_mov_b32_e32 v35, v17
	v_mov_b32_e32 v33, v17
	v_lshl_add_u64 v[0:1], s[6:7], 0, v[0:1]
	s_mov_b32 s6, 0x3a800000
	v_mov_b32_e32 v31, v17
	v_mov_b32_e32 v25, v17
	s_waitcnt vmcnt(9)
	v_add_f32_e32 v2, v40, v41
	s_waitcnt vmcnt(8)
	v_add_f32_e32 v3, v44, v45
	v_add_f32_e32 v2, v2, v42
	s_waitcnt vmcnt(7)
	v_add_f32_e32 v5, v48, v49
	v_add_f32_e32 v3, v3, v46
	v_add_f32_e32 v2, v2, v43
	s_waitcnt vmcnt(4)
	v_add_f32_e32 v15, v60, v61
	v_add_f32_e32 v11, v52, v53
	v_add_f32_e32 v5, v5, v50
	v_add_f32_e32 v3, v3, v47
	s_waitcnt vmcnt(3)
	v_add_f32_e32 v16, v64, v65
	v_add_f32_e32 v2, 0, v2
	v_add_f32_e32 v15, v15, v62
	v_add_f32_e32 v11, v11, v54
	v_add_f32_e32 v5, v5, v51
	s_waitcnt vmcnt(2)
	v_add_f32_e32 v21, v68, v69
	v_add_f32_e32 v16, v16, v66
	v_add_f32_e32 v2, v2, v3
	v_add_f32_e32 v3, v15, v63
	v_add_f32_e32 v13, v56, v57
	v_add_f32_e32 v11, v11, v55
	v_add_f32_e32 v21, v21, v70
	v_add_f32_e32 v15, v16, v67
	v_add_f32_e32 v2, v2, v5
	v_add_f32_e32 v3, 0, v3
	v_add_f32_e32 v13, v13, v58
	v_add_f32_e32 v16, v21, v71
	v_add_f32_e32 v2, v2, v11
	v_add_f32_e32 v3, v3, v15
	v_add_f32_e32 v13, v13, v59
	v_add_f32_dpp v2, v2, v2 quad_perm:[1,0,3,2] row_mask:0xf bank_mask:0xf bound_ctrl:1
	v_add_f32_e32 v3, v3, v16
	v_add_f32_e32 v3, v3, v13
	v_add_f32_dpp v2, v2, v2 quad_perm:[2,3,0,1] row_mask:0xf bank_mask:0xf bound_ctrl:1
	s_nop 0
	v_add_f32_dpp v3, v3, v3 quad_perm:[1,0,3,2] row_mask:0xf bank_mask:0xf bound_ctrl:1
	v_add_f32_dpp v2, v2, v2 row_half_mirror row_mask:0xf bank_mask:0xf bound_ctrl:1
	s_nop 0
	v_add_f32_dpp v3, v3, v3 quad_perm:[2,3,0,1] row_mask:0xf bank_mask:0xf bound_ctrl:1
	v_add_f32_dpp v2, v2, v2 row_mirror row_mask:0xf bank_mask:0xf bound_ctrl:1
	v_mov_b32_e32 v5, v2
	v_add_f32_dpp v3, v3, v3 row_half_mirror row_mask:0xf bank_mask:0xf bound_ctrl:1
	s_nop 0
	v_permlane16_swap_b32_e32 v2, v5
	v_add_f32_dpp v3, v3, v3 row_mirror row_mask:0xf bank_mask:0xf bound_ctrl:1
	v_add_f32_e32 v2, v2, v5
	v_mov_b32_e32 v5, v3
	v_mov_b32_e32 v11, v2
	s_nop 0
	v_permlane16_swap_b32_e32 v3, v5
	v_permlane32_swap_b32_e32 v2, v11
	v_add_f32_e32 v3, v3, v5
	v_add_f32_e32 v2, v2, v11
	v_mov_b32_e32 v5, v3
	v_mul_f32_e32 v2, 0x3a800000, v2
	v_mov_b32_e32 v100, v2
	s_nop 0
	v_permlane32_swap_b32_e32 v3, v5
	v_pk_add_f32 v[40:41], v[40:41], v[2:3] op_sel_hi:[1,0] neg_lo:[0,1] neg_hi:[0,1]
	v_pk_add_f32 v[80:81], v[44:45], v[2:3] op_sel_hi:[1,0] neg_lo:[0,1] neg_hi:[0,1]
	v_pk_add_f32 v[42:43], v[42:43], v[2:3] op_sel_hi:[1,0] neg_lo:[0,1] neg_hi:[0,1]
	v_pk_add_f32 v[82:83], v[46:47], v[2:3] op_sel_hi:[1,0] neg_lo:[0,1] neg_hi:[0,1]
	v_pk_add_f32 v[48:49], v[48:49], v[2:3] op_sel_hi:[1,0] neg_lo:[0,1] neg_hi:[0,1]
	v_pk_add_f32 v[50:51], v[50:51], v[2:3] op_sel_hi:[1,0] neg_lo:[0,1] neg_hi:[0,1]
	v_pk_add_f32 v[52:53], v[52:53], v[2:3] op_sel_hi:[1,0] neg_lo:[0,1] neg_hi:[0,1]
	v_pk_add_f32 v[54:55], v[54:55], v[2:3] op_sel_hi:[1,0] neg_lo:[0,1] neg_hi:[0,1]
	v_add_f32_e32 v5, v3, v5
	v_pk_mul_f32 v[2:3], v[40:41], v[40:41]
	v_pk_mul_f32 v[46:47], v[80:81], v[80:81]
	v_pk_mul_f32 v[44:45], v[42:43], v[42:43]
	v_pk_mul_f32 v[84:85], v[82:83], v[82:83]
	v_pk_mul_f32 v[86:87], v[48:49], v[48:49]
	v_mul_f32_e32 v16, 0x3a800000, v5
	v_mov_b32_e32 v102, v16
	v_add_f32_e32 v5, v46, v47
	v_add_f32_e32 v2, v2, v3
	v_pk_mul_f32 v[88:89], v[50:51], v[50:51]
	v_pk_mul_f32 v[90:91], v[52:53], v[52:53]
	v_add_f32_e32 v3, v86, v87
	v_add_f32_e32 v5, v84, v5
	v_add_f32_e32 v2, v44, v2
	v_pk_mul_f32 v[92:93], v[54:55], v[54:55]
	v_add_f32_e32 v11, v90, v91
	v_add_f32_e32 v3, v88, v3
	v_add_f32_e32 v5, v85, v5
	v_add_f32_e32 v2, v45, v2
	v_add_f32_e32 v11, v92, v11
	v_add_f32_e32 v3, v89, v3
	v_add_f32_e32 v2, v2, v5
	v_add_f32_e32 v11, v93, v11
	v_add_f32_e32 v2, v3, v2
	v_add_f32_e32 v2, v11, v2
	v_pk_add_f32 v[46:47], v[60:61], v[16:17] op_sel_hi:[1,0] neg_lo:[0,1] neg_hi:[0,1]
	v_pk_add_f32 v[64:65], v[64:65], v[16:17] op_sel_hi:[1,0] neg_lo:[0,1] neg_hi:[0,1]
	v_add_f32_dpp v2, v2, v2 quad_perm:[1,0,3,2] row_mask:0xf bank_mask:0xf bound_ctrl:1
	v_pk_add_f32 v[60:61], v[62:63], v[16:17] op_sel_hi:[1,0] neg_lo:[0,1] neg_hi:[0,1]
	v_pk_mul_f32 v[62:63], v[46:47], v[46:47]
	v_add_f32_dpp v2, v2, v2 quad_perm:[2,3,0,1] row_mask:0xf bank_mask:0xf bound_ctrl:1
	v_pk_add_f32 v[66:67], v[66:67], v[16:17] op_sel_hi:[1,0] neg_lo:[0,1] neg_hi:[0,1]
	v_pk_mul_f32 v[86:87], v[64:65], v[64:65]
	v_add_f32_dpp v2, v2, v2 row_half_mirror row_mask:0xf bank_mask:0xf bound_ctrl:1
	v_pk_mul_f32 v[84:85], v[60:61], v[60:61]
	v_pk_mul_f32 v[88:89], v[66:67], v[66:67]
	v_add_f32_dpp v2, v2, v2 row_mirror row_mask:0xf bank_mask:0xf bound_ctrl:1
	v_mov_b32_e32 v3, v2
	s_nop 1
	v_permlane16_swap_b32_e32 v2, v3
	v_add_f32_e32 v3, v2, v3
	v_add_f32_e32 v2, v86, v87
	v_add_f32_e32 v5, v62, v63
	v_pk_add_f32 v[68:69], v[68:69], v[16:17] op_sel_hi:[1,0] neg_lo:[0,1] neg_hi:[0,1]
; DI bf16x4 pack4(float a, float b, float c, float d) { u32x2v u; u.x = pk2(a, b); u.y = pk2(c, d); return __builtin_bit_cast(bf16x4, u); }
; DI float wave_sum(float x) { x = row_sum16(x); F2 a = swap16(x); x = a.lo + a.hi; F2 b = swap32(x); return b.lo + b.hi; }
; DI void ln_rows2(const float* s0, const float* s1, const float* g, const float* b, float* d0, bf16_t* db0, float* d1, bf16_t* db1, int lane) {
;     ...
;   q0 = wave_sum(q0); q1 = wave_sum(q1);
;   const float r0 = rsqrtf(q0 * (1.f / 1024.f) + LN_EPS), r1 = rsqrtf(q1 * (1.f / 1024.f) + LN_EPS);
; #pragma unroll
;   for (int i = 0; i < 4; ++i) {
;     const float4 gg = reinterpret_cast<const float4*>(g)[lane + 64 * i], bb = reinterpret_cast<const float4*>(b)[lane + 64 * i];
;     float4 o;
;     o.x = (v0[i].x - mu0) * r0 * gg.x + bb.x; o.y = (v0[i].y - mu0) * r0 * gg.y + bb.y; o.z = (v0[i].z - mu0) * r0 * gg.z + bb.z; o.w = (v0[i].w - mu0) * r0 * gg.w + bb.w;
;     reinterpret_cast<float4*>(d0)[lane + 64 * i] = o; st4(db0 + 4 * (lane + 64 * i), pack4(o.x, o.y, o.z, o.w));
;     o.x = (v1[i].x - mu1) * r1 * gg.x + bb.x; o.y = (v1[i].y - mu1) * r1 * gg.y + bb.y; o.z = (v1[i].z - mu1) * r1 * gg.z + bb.z; o.w = (v1[i].w - mu1) * r1 * gg.w + bb.w;
;     reinterpret_cast<float4*>(d1)[lane + 64 * i] = o; st4(db1 + 4 * (lane + 64 * i), pack4(o.x, o.y, o.z, o.w));
;   }
; }
	v_add_f32_e32 v2, v88, v2
	v_add_f32_e32 v5, v84, v5
	v_pk_add_f32 v[70:71], v[70:71], v[16:17] op_sel_hi:[1,0] neg_lo:[0,1] neg_hi:[0,1]
	v_pk_mul_f32 v[90:91], v[68:69], v[68:69]
	v_add_f32_e32 v2, v89, v2
	v_add_f32_e32 v5, v85, v5
	v_pk_mul_f32 v[92:93], v[70:71], v[70:71]
	v_add_f32_e32 v2, v5, v2
	v_add_f32_e32 v5, v90, v91
	v_pk_add_f32 v[56:57], v[56:57], v[16:17] op_sel_hi:[1,0] neg_lo:[0,1] neg_hi:[0,1]
	v_add_f32_e32 v5, v92, v5
	v_pk_add_f32 v[58:59], v[58:59], v[16:17] op_sel_hi:[1,0] neg_lo:[0,1] neg_hi:[0,1]
	v_pk_mul_f32 v[94:95], v[56:57], v[56:57]
	v_add_f32_e32 v5, v93, v5
	v_pk_mul_f32 v[96:97], v[58:59], v[58:59]
	v_add_f32_e32 v2, v5, v2
	v_add_f32_e32 v5, v94, v95
	v_add_f32_e32 v5, v96, v5
	v_add_f32_e32 v5, v97, v5
	v_add_f32_e32 v2, v5, v2
	v_mov_b32_e32 v45, v3
	s_nop 1
	v_permlane32_swap_b32_e32 v3, v45
	v_add_f32_dpp v2, v2, v2 quad_perm:[1,0,3,2] row_mask:0xf bank_mask:0xf bound_ctrl:1
	s_nop 1
	v_add_f32_dpp v2, v2, v2 quad_perm:[2,3,0,1] row_mask:0xf bank_mask:0xf bound_ctrl:1
	s_nop 1
	v_add_f32_dpp v2, v2, v2 row_half_mirror row_mask:0xf bank_mask:0xf bound_ctrl:1
	s_nop 1
	v_add_f32_dpp v2, v2, v2 row_mirror row_mask:0xf bank_mask:0xf bound_ctrl:1
	v_mov_b32_e32 v5, v2
	s_nop 1
	v_permlane16_swap_b32_e32 v2, v5
	v_add_f32_e32 v2, v2, v5
	v_mov_b32_e32 v44, v2
	s_nop 1
	v_permlane32_swap_b32_e32 v2, v44
	v_pk_add_f32 v[2:3], v[2:3], v[44:45]
	v_lshl_add_u64 v[44:45], v[28:29], 0, v[34:35]
	v_pk_fma_f32 v[2:3], v[2:3], s[6:7], v[152:153] op_sel_hi:[1,0,0]
	s_mov_b32 s6, 0x800000
	v_mul_f32_e32 v5, 0x4b800000, v3
	v_cmp_gt_f32_e32 vcc, s6, v3
	v_lshl_add_u64 v[34:35], v[0:1], 0, v[34:35]
	s_nop 0
	v_cndmask_b32_e32 v3, v3, v5, vcc
	v_rsq_f32_e32 v3, v3
	s_nop 0
	v_mul_f32_e32 v5, 0x45800000, v3
	v_cndmask_b32_e32 v16, v3, v5, vcc
	v_mul_f32_e32 v3, 0x4b800000, v2
	v_cmp_gt_f32_e32 vcc, s6, v2
	v_pk_mul_f32 v[40:41], v[40:41], v[16:17] op_sel_hi:[1,0]
	v_pk_mul_f32 v[42:43], v[42:43], v[16:17] op_sel_hi:[1,0]
	v_cndmask_b32_e32 v2, v2, v3, vcc
	v_rsq_f32_e32 v5, v2
	s_waitcnt vmcnt(0)
	v_pk_fma_f32 v[40:41], v[72:73], v[40:41], v[76:77]
	v_pk_fma_f32 v[42:43], v[74:75], v[42:43], v[78:79]
	v_cvt_pk_bf16_f32 v2, v40, v41
	v_mul_f32_e32 v11, 0x45800000, v5
	v_cndmask_b32_e32 v62, v5, v11, vcc
	v_cvt_pk_bf16_f32 v3, v42, v43
	s_and_saveexec_b64 s[62:63], s[60:61]
	global_store_dwordx4 v[36:37], v[40:43], off
	s_mov_b64 exec, s[62:63]
	v_pk_mul_f32 v[64:65], v[64:65], v[62:63] op_sel_hi:[1,0]
	v_pk_mul_f32 v[66:67], v[66:67], v[62:63] op_sel_hi:[1,0]
	v_pk_mul_f32 v[40:41], v[46:47], v[62:63] op_sel_hi:[1,0]
	v_pk_mul_f32 v[42:43], v[60:61], v[62:63] op_sel_hi:[1,0]
	v_pk_fma_f32 v[40:41], v[72:73], v[40:41], v[76:77]
	v_pk_fma_f32 v[42:43], v[74:75], v[42:43], v[78:79]
	v_cvt_pk_bf16_f32 v46, v40, v41
	v_cvt_pk_bf16_f32 v47, v42, v43
	global_store_dwordx2 v[44:45], v[2:3], off
	s_and_saveexec_b64 s[62:63], s[60:61]
	global_store_dwordx4 v[38:39], v[40:43], off
	s_mov_b64 exec, s[62:63]
	global_store_dwordx2 v[34:35], v[46:47], off
	global_load_dwordx4 v[40:43], v[6:7], off offset:1024
	s_nop 0
	global_load_dwordx4 v[44:47], v[8:9], off offset:1024
	v_lshl_add_u64 v[2:3], v[28:29], 0, v[32:33]
	v_lshl_add_u64 v[60:61], v[0:1], 0, v[32:33]
	v_pk_mul_f32 v[32:33], v[80:81], v[16:17] op_sel_hi:[1,0]
	v_pk_mul_f32 v[34:35], v[82:83], v[16:17] op_sel_hi:[1,0]
	s_waitcnt vmcnt(0)
	v_pk_fma_f32 v[32:33], v[32:33], v[40:41], v[44:45]
	v_pk_fma_f32 v[34:35], v[34:35], v[42:43], v[46:47]
	v_pk_fma_f32 v[40:41], v[64:65], v[40:41], v[44:45]
	v_pk_fma_f32 v[42:43], v[66:67], v[42:43], v[46:47]
	s_and_saveexec_b64 s[62:63], s[60:61]
	global_store_dwordx4 v[36:37], v[32:35], off offset:1024
	s_mov_b64 exec, s[62:63]
	v_lshl_add_u64 v[46:47], v[0:1], 0, v[30:31]
	v_pk_mul_f32 v[0:1], v[48:49], v[16:17] op_sel_hi:[1,0]
	v_cvt_pk_bf16_f32 v32, v32, v33
	v_cvt_pk_bf16_f32 v33, v34, v35
	v_cvt_pk_bf16_f32 v34, v40, v41
	v_cvt_pk_bf16_f32 v35, v42, v43
	global_store_dwordx2 v[2:3], v[32:33], off
	s_and_saveexec_b64 s[62:63], s[60:61]
	global_store_dwordx4 v[38:39], v[40:43], off offset:1024
	s_mov_b64 exec, s[62:63]
	global_store_dwordx2 v[60:61], v[34:35], off
	global_load_dwordx4 v[32:35], v[6:7], off offset:2048
	s_nop 0
	global_load_dwordx4 v[40:43], v[8:9], off offset:2048
	v_pk_mul_f32 v[2:3], v[50:51], v[16:17] op_sel_hi:[1,0]
	v_lshl_add_u64 v[44:45], v[28:29], 0, v[30:31]
	v_pk_mul_f32 v[30:31], v[68:69], v[62:63] op_sel_hi:[1,0]
	v_pk_mul_f32 v[48:49], v[70:71], v[62:63] op_sel_hi:[1,0]
	v_lshl_add_u64 v[28:29], v[28:29], 0, v[24:25]
	s_waitcnt vmcnt(0)
	v_pk_fma_f32 v[0:1], v[0:1], v[32:33], v[40:41]
	v_pk_fma_f32 v[2:3], v[2:3], v[34:35], v[42:43]
	v_pk_fma_f32 v[30:31], v[30:31], v[32:33], v[40:41]
	v_pk_fma_f32 v[32:33], v[48:49], v[34:35], v[42:43]
	s_and_saveexec_b64 s[62:63], s[60:61]
	global_store_dwordx4 v[36:37], v[0:3], off offset:2048
	s_mov_b64 exec, s[62:63]
	v_pk_mul_f32 v[34:35], v[52:53], v[16:17] op_sel_hi:[1,0]
	v_pk_mul_f32 v[48:49], v[58:59], v[62:63] op_sel_hi:[1,0]
	v_cvt_pk_bf16_f32 v0, v0, v1
	v_cvt_pk_bf16_f32 v1, v2, v3
	v_cvt_pk_bf16_f32 v2, v30, v31
	v_cvt_pk_bf16_f32 v3, v32, v33
	global_store_dwordx2 v[44:45], v[0:1], off
	s_and_saveexec_b64 s[62:63], s[60:61]
	global_store_dwordx4 v[38:39], v[30:33], off offset:2048
	s_mov_b64 exec, s[62:63]
	global_store_dwordx2 v[46:47], v[2:3], off
	global_load_dwordx4 v[0:3], v[6:7], off offset:3072
	s_nop 0
	global_load_dwordx4 v[30:33], v[8:9], off offset:3072
	v_pk_mul_f32 v[44:45], v[54:55], v[16:17] op_sel_hi:[1,0]
	v_pk_mul_f32 v[46:47], v[56:57], v[62:63] op_sel_hi:[1,0]
	v_lshlrev_b64 v[40:41], 10, v[26:27]
	s_waitcnt vmcnt(0)
	v_pk_fma_f32 v[42:43], v[34:35], v[0:1], v[30:31]
	v_pk_fma_f32 v[44:45], v[44:45], v[2:3], v[32:33]
	v_pk_fma_f32 v[0:1], v[46:47], v[0:1], v[30:31]
	v_pk_fma_f32 v[2:3], v[48:49], v[2:3], v[32:33]
	v_cvt_pk_bf16_f32 v30, v42, v43
	v_cvt_pk_bf16_f32 v31, v44, v45
	s_and_saveexec_b64 s[62:63], s[60:61]
	global_store_dwordx4 v[36:37], v[42:45], off offset:3072
	s_mov_b64 exec, s[62:63]
	global_store_dwordx2 v[28:29], v[30:31], off
	s_and_saveexec_b64 s[62:63], s[60:61]
	global_store_dwordx4 v[38:39], v[0:3], off offset:3072
	s_mov_b64 exec, s[62:63]
	v_mov_b32_e32 v101, v16
	v_mov_b32_e32 v103, v62
	v_lshlrev_b32_e32 v104, 3, v26
	global_store_dwordx2 v104, v[100:101], s[58:59]
	global_store_dwordx2 v104, v[102:103], s[56:57]
	s_branch .LBB0_2767
